# diff attention: stale running max detected from the partial row sums (no per-tile max pass); rare path recomputes the scores and rescales
# speedup vs baseline: 1.0342x; 1.0013x over previous
.LBB0_783:
	v_readlane_b32 s3, v251, 25
	s_ashr_i32 s0, s3, 7
	s_ashr_i32 s1, s0, 31
	s_lshl_b64 s[8:9], s[0:1], 14
	v_writelane_b32 v251, s8, 32
	s_lshl_b32 s1, s3, 8
	s_and_b32 s1, s1, 0x1f00
	v_writelane_b32 v251, s9, 33
	s_bfe_u32 s2, s3, 0x20005
	v_writelane_b32 v251, s1, 34
	s_xor_b32 s1, s1, 0x3f00
	v_writelane_b32 v251, s1, 36
	s_lshl_b32 s1, s2, 8
	s_mul_i32 s4, s0, 0xc000000
	s_mul_hi_i32 s3, s0, 0xc000000
	s_add_u32 s0, s48, s4
	v_writelane_b32 v251, s1, 38
	s_addc_u32 s1, s49, s3
	s_add_u32 s40, s0, 0x2000
	s_addc_u32 s41, s1, 0
	s_lshl_b32 s8, s2, 9
	s_mov_b32 s9, s5
	v_writelane_b32 v251, s8, 40
	s_add_u32 s0, s0, s8
	s_addc_u32 s1, s1, 0
	v_writelane_b32 v251, s9, 41
	s_add_u32 s8, s0, 0x2800
	v_readlane_b32 s0, v251, 8
	s_addc_u32 s9, s1, 0
	v_mbcnt_lo_u32_b32 v0, -1, 0
	v_mbcnt_hi_u32_b32 v0, -1, v0
	s_lshl_b32 s2, s2, 10
	v_add_u32_e32 v208, s0, v0
	s_mov_b64 s[0:1], s[68:69]
	s_load_dwordx2 s[0:1], s[0:1], 0x88
	v_and_b32_e32 v2, 63, v0
	v_lshlrev_b32_e32 v5, 4, v0
	s_waitcnt lgkmcnt(0)
	v_lshlrev_b32_e32 v4, 3, v2
	v_and_b32_e32 v6, 0xc0, v5
	s_add_u32 s0, s0, s2
	v_lshlrev_b32_e32 v7, 1, v0
	s_addc_u32 s1, s1, 0
	v_and_or_b32 v6, v4, 24, v6
	v_and_b32_e32 v7, 32, v7
	v_and_b32_e32 v4, 0x100, v4
	v_bfe_u32 v212, v0, 4, 2
	s_add_u32 s42, s0, 0x37e00000
	v_bfe_u32 v1, v0, 5, 1
	v_or3_b32 v4, v6, v7, v4
	v_bitop3_b32 v7, v212, v0, 15 bitop3:0x78
	s_addc_u32 s43, s1, 0
	v_lshlrev_b32_e32 v210, 2, v1
	v_lshlrev_b32_e32 v213, 4, v7
	v_lshlrev_b32_e32 v7, 4, v1
	v_lshrrev_b32_e32 v1, 1, v0
	v_and_b32_e32 v209, 31, v0
	v_and_b32_e32 v215, 8, v1
	v_lshlrev_b32_e32 v1, 3, v0
	s_cmp_lg_u32 0, -1
	v_mul_u32_u24_e32 v3, 0x3000, v209
	v_and_b32_e32 v1, 24, v1
	s_cselect_b32 s2, 0, 0
	s_movk_i32 s0, 0x70
	v_and_b32_e32 v6, 15, v0
	v_or_b32_e32 v194, v7, v3
	v_bfe_u32 v214, v0, 2, 3
	v_and_or_b32 v216, v0, 32, v1
	v_add_u32_e32 v217, s2, v4
	v_lshlrev_b32_e32 v0, 8, v209
	v_and_b32_e32 v3, 0x70, v5
	s_add_i32 s1, s2, 0x10000
	v_bitop3_b32 v5, v7, v5, s0 bitop3:0x78
	s_movk_i32 s0, 0x60
	s_add_i32 s2, s2, 0x14000
	v_add_u32_e32 v4, s1, v0
	v_bitop3_b32 v8, v7, v3, 32 bitop3:0x36
	v_bitop3_b32 v9, v7, v3, 64 bitop3:0x36
	v_bitop3_b32 v3, v7, v3, s0 bitop3:0x36
	v_add_u32_e32 v0, s2, v0
	v_add_u32_e32 v222, v5, v0
	v_add_u32_e32 v223, v8, v0
	v_add_u32_e32 v224, v9, v0
	v_add_u32_e32 v225, v3, v0
	v_mul_u32_u24_e32 v0, 0x3000, v212
	s_movk_i32 s44, 0x3000
	v_mov_b32_e32 v1, 0
	v_cmp_gt_u32_e64 s[0:1], 32, v2
	s_add_u32 s6, s6, s4
	v_mov_b32_e32 v2, 0xc000
	v_or_b32_e32 v227, v0, v213
	v_bitop3_b32 v0, v212, v6, 4 bitop3:0x36
	v_sub_u32_e32 v211, v209, v210
	v_mov_b32_e32 v195, v1
	v_add_u32_e32 v218, v5, v4
	v_add_u32_e32 v219, v8, v4
	v_add_u32_e32 v220, v9, v4
	v_add_u32_e32 v221, v3, v4
	v_writelane_b32 v251, s4, 42
	s_addc_u32 s7, s7, s3
	v_mad_u32_u24 v226, v212, s44, v2
	v_lshlrev_b32_e32 v228, 4, v0
	v_mov_b32_e32 v229, 0x7ffffff3
	s_movk_i32 s45, 0x1800
	s_mov_b64 s[10:11], 0x1fec2000
	s_mov_b64 s[12:13], 0x1fec2800
	s_mov_b64 s[14:15], 0x1fec2880
	s_mov_b64 s[16:17], 0x1fec2900
	s_mov_b64 s[18:19], 0x1fec2980
	s_brev_b32 s46, -3
	s_mov_b32 s47, 0x41000000
	s_mov_b64 s[20:21], 0x1ff82000
	s_mov_b64 s[22:23], 0x1ff82800
	s_mov_b64 s[24:25], 0x1ff82880
	s_mov_b64 s[26:27], 0x1ff82900
	s_mov_b64 s[28:29], 0x1ff82980
	s_mov_b32 s50, 0x7fffe000
	v_mov_b32_e32 v230, 0xff800000
	s_mov_b32 s51, 0
	s_waitcnt vmcnt(63) expcnt(7) lgkmcnt(15)
	v_mbcnt_lo_u32_b32 v238, -1, 0
	v_mbcnt_hi_u32_b32 v238, -1, v238
	v_and_b32_e32 v239, 15, v238
	v_lshrrev_b32_e32 v240, 4, v238
	v_and_b32_e32 v241, 3, v238
	v_bfe_u32 v242, v238, 2, 2
	v_lshrrev_b32_e32 v243, 1, v240
	v_lshlrev_b32_e32 v217, 12, v243
	v_and_b32_e32 v243, 1, v240
	v_lshl_or_b32 v217, v243, 7, v217
	v_lshl_or_b32 v217, v242, 5, v217
	v_lshl_or_b32 v217, v241, 3, v217
	v_xor_b32_e32 v243, v240, v241
	v_lshlrev_b32_e32 v218, 8, v239
	v_lshl_or_b32 v218, v243, 4, v218
	v_bfe_u32 v243, v238, 2, 1
	v_lshl_or_b32 v218, v243, 6, v218
	v_or_b32_e32 v218, 0x10000, v218
	v_xor_b32_e32 v219, 64, v218
	v_bfe_u32 v243, v238, 1, 3
	v_mul_u32_u24_e32 v220, 0x3000, v243
	v_lshl_or_b32 v220, v240, 5, v220
	v_and_b32_e32 v243, 1, v238
	v_lshl_or_b32 v220, v243, 4, v220
	v_lshlrev_b32_e32 v243, 2, v240
	v_sub_u32_e32 v221, v239, v243
	v_mul_u32_u24_e32 v194, 0x3000, v239
	v_lshl_or_b32 v194, v240, 4, v194
	v_add_u32_e32 v194, 0x1800, v194
	v_mov_b32_e32 v195, 0
	v_xor_b32_e32 v224, 16, v238
	v_lshlrev_b32_e32 v224, 2, v224
	v_cmp_gt_u32_e64 s[0:1], 16, v238
	s_mov_b32 s82, 0x453a4f54
	s_barrier
	v_writelane_b32 v251, s3, 43
	s_branch .LBB0_785

.LBB0_790:
	s_sub_i32 s73, s56, 158
	s_cmp_gt_i32 s73, s4
	s_cbranch_scc1 .Ld16a_end0
	s_cmp_eq_u32 s57, 2
	s_cbranch_scc1 .Ld16a_rd0
	ds_read_b128 v[252:255], v219 offset:128
	s_waitcnt lgkmcnt(3)
	v_mfma_f32_16x16x32_bf16 v[130:133], v[238:241], v[162:165], 0
	v_mfma_f32_16x16x32_bf16 v[146:149], v[238:241], v[178:181], 0
	ds_read_b128 v[238:241], v218 offset:4096
	s_waitcnt lgkmcnt(3)
	v_mfma_f32_16x16x32_bf16 v[130:133], v[242:245], v[166:169], v[130:133]
	v_mfma_f32_16x16x32_bf16 v[146:149], v[242:245], v[182:185], v[146:149]
	ds_read_b128 v[242:245], v219 offset:4096
	s_waitcnt lgkmcnt(3)
	v_mfma_f32_16x16x32_bf16 v[130:133], v[246:249], v[170:173], v[130:133]
	v_mfma_f32_16x16x32_bf16 v[146:149], v[246:249], v[186:189], v[146:149]
	ds_read_b128 v[246:249], v218 offset:4224
	s_waitcnt lgkmcnt(3)
	v_mfma_f32_16x16x32_bf16 v[130:133], v[252:255], v[174:177], v[130:133]
	v_mfma_f32_16x16x32_bf16 v[146:149], v[252:255], v[190:193], v[146:149]
	ds_read_b128 v[252:255], v219 offset:4224
	s_waitcnt lgkmcnt(3)
	v_mfma_f32_16x16x32_bf16 v[134:137], v[238:241], v[162:165], 0
	v_mfma_f32_16x16x32_bf16 v[150:153], v[238:241], v[178:181], 0
	ds_read_b128 v[238:241], v218 offset:8192
	s_waitcnt lgkmcnt(3)
	v_mfma_f32_16x16x32_bf16 v[134:137], v[242:245], v[166:169], v[134:137]
	v_mfma_f32_16x16x32_bf16 v[150:153], v[242:245], v[182:185], v[150:153]
	ds_read_b128 v[242:245], v219 offset:8192
	s_waitcnt lgkmcnt(3)
	v_mfma_f32_16x16x32_bf16 v[134:137], v[246:249], v[170:173], v[134:137]
	v_mfma_f32_16x16x32_bf16 v[150:153], v[246:249], v[186:189], v[150:153]
	ds_read_b128 v[246:249], v218 offset:8320
	s_waitcnt lgkmcnt(3)
	v_mfma_f32_16x16x32_bf16 v[134:137], v[252:255], v[174:177], v[134:137]
	v_mfma_f32_16x16x32_bf16 v[150:153], v[252:255], v[190:193], v[150:153]
	ds_read_b128 v[252:255], v219 offset:8320
	s_waitcnt lgkmcnt(3)
	v_mfma_f32_16x16x32_bf16 v[138:141], v[238:241], v[162:165], 0
	v_mfma_f32_16x16x32_bf16 v[154:157], v[238:241], v[178:181], 0
	ds_read_b128 v[238:241], v218 offset:12288
	s_waitcnt lgkmcnt(3)
	v_mfma_f32_16x16x32_bf16 v[138:141], v[242:245], v[166:169], v[138:141]
	v_mfma_f32_16x16x32_bf16 v[154:157], v[242:245], v[182:185], v[154:157]
	ds_read_b128 v[242:245], v219 offset:12288
	s_waitcnt lgkmcnt(3)
	v_mfma_f32_16x16x32_bf16 v[138:141], v[246:249], v[170:173], v[138:141]
	v_mfma_f32_16x16x32_bf16 v[154:157], v[246:249], v[186:189], v[154:157]
	ds_read_b128 v[246:249], v218 offset:12416
	s_waitcnt lgkmcnt(3)
	v_mfma_f32_16x16x32_bf16 v[138:141], v[252:255], v[174:177], v[138:141]
	v_mfma_f32_16x16x32_bf16 v[154:157], v[252:255], v[190:193], v[154:157]
	ds_read_b128 v[252:255], v219 offset:12416
	s_waitcnt lgkmcnt(3)
	v_mfma_f32_16x16x32_bf16 v[142:145], v[238:241], v[162:165], 0
	v_mfma_f32_16x16x32_bf16 v[158:161], v[238:241], v[178:181], 0
	s_waitcnt lgkmcnt(2)
	v_mfma_f32_16x16x32_bf16 v[142:145], v[242:245], v[166:169], v[142:145]
	v_mfma_f32_16x16x32_bf16 v[158:161], v[242:245], v[182:185], v[158:161]
	s_waitcnt lgkmcnt(1)
	v_mfma_f32_16x16x32_bf16 v[142:145], v[246:249], v[170:173], v[142:145]
	v_mfma_f32_16x16x32_bf16 v[158:161], v[246:249], v[186:189], v[158:161]
	s_waitcnt lgkmcnt(0)
	v_mfma_f32_16x16x32_bf16 v[142:145], v[252:255], v[174:177], v[142:145]
	v_mfma_f32_16x16x32_bf16 v[158:161], v[252:255], v[190:193], v[158:161]
	s_nop 7
	s_nop 1
	s_sub_i32 s36, s56, 64
	s_cmp_le_i32 s36, s4
	s_cbranch_scc1 .Ld16a_nma0
	v_cmp_gt_i32_e64 s[74:75], 0, v233
	v_cmp_gt_i32_e64 s[76:77], 1, v233
	v_cmp_gt_i32_e64 s[78:79], 2, v233
	v_cmp_gt_i32_e64 s[80:81], 3, v233
	v_cndmask_b32_e64 v130, v130, v230, s[74:75]
	v_cndmask_b32_e64 v131, v131, v230, s[76:77]
	v_cndmask_b32_e64 v132, v132, v230, s[78:79]
	v_cndmask_b32_e64 v133, v133, v230, s[80:81]
	v_cmp_gt_i32_e64 s[74:75], 16, v233
	v_cmp_gt_i32_e64 s[76:77], 17, v233
	v_cmp_gt_i32_e64 s[78:79], 18, v233
	v_cmp_gt_i32_e64 s[80:81], 19, v233
	v_cndmask_b32_e64 v134, v134, v230, s[74:75]
	v_cndmask_b32_e64 v135, v135, v230, s[76:77]
	v_cndmask_b32_e64 v136, v136, v230, s[78:79]
	v_cndmask_b32_e64 v137, v137, v230, s[80:81]
	v_cmp_gt_i32_e64 s[74:75], 32, v233
	v_cmp_gt_i32_e64 s[76:77], 33, v233
	v_cmp_gt_i32_e64 s[78:79], 34, v233
	v_cmp_gt_i32_e64 s[80:81], 35, v233
	v_cndmask_b32_e64 v138, v138, v230, s[74:75]
	v_cndmask_b32_e64 v139, v139, v230, s[76:77]
	v_cndmask_b32_e64 v140, v140, v230, s[78:79]
	v_cndmask_b32_e64 v141, v141, v230, s[80:81]
	v_cmp_gt_i32_e64 s[74:75], 48, v233
	v_cmp_gt_i32_e64 s[76:77], 49, v233
	v_cmp_gt_i32_e64 s[78:79], 50, v233
	v_cmp_gt_i32_e64 s[80:81], 51, v233
	v_cndmask_b32_e64 v142, v142, v230, s[74:75]
	v_cndmask_b32_e64 v143, v143, v230, s[76:77]
	v_cndmask_b32_e64 v144, v144, v230, s[78:79]
	v_cndmask_b32_e64 v145, v145, v230, s[80:81]
	v_cmp_gt_i32_e64 s[74:75], -16, v233
	v_cmp_gt_i32_e64 s[76:77], -15, v233
	v_cmp_gt_i32_e64 s[78:79], -14, v233
	v_cmp_gt_i32_e64 s[80:81], -13, v233
	v_cndmask_b32_e64 v146, v146, v230, s[74:75]
	v_cndmask_b32_e64 v147, v147, v230, s[76:77]
	v_cndmask_b32_e64 v148, v148, v230, s[78:79]
	v_cndmask_b32_e64 v149, v149, v230, s[80:81]
	v_cmp_gt_i32_e64 s[74:75], 0, v233
	v_cmp_gt_i32_e64 s[76:77], 1, v233
	v_cmp_gt_i32_e64 s[78:79], 2, v233
	v_cmp_gt_i32_e64 s[80:81], 3, v233
	v_cndmask_b32_e64 v150, v150, v230, s[74:75]
	v_cndmask_b32_e64 v151, v151, v230, s[76:77]
	v_cndmask_b32_e64 v152, v152, v230, s[78:79]
	v_cndmask_b32_e64 v153, v153, v230, s[80:81]
	v_cmp_gt_i32_e64 s[74:75], 16, v233
	v_cmp_gt_i32_e64 s[76:77], 17, v233
	v_cmp_gt_i32_e64 s[78:79], 18, v233
	v_cmp_gt_i32_e64 s[80:81], 19, v233
	v_cndmask_b32_e64 v154, v154, v230, s[74:75]
	v_cndmask_b32_e64 v155, v155, v230, s[76:77]
	v_cndmask_b32_e64 v156, v156, v230, s[78:79]
	v_cndmask_b32_e64 v157, v157, v230, s[80:81]
	v_cmp_gt_i32_e64 s[74:75], 32, v233
	v_cmp_gt_i32_e64 s[76:77], 33, v233
	v_cmp_gt_i32_e64 s[78:79], 34, v233
	v_cmp_gt_i32_e64 s[80:81], 35, v233
	v_cndmask_b32_e64 v158, v158, v230, s[74:75]
	v_cndmask_b32_e64 v159, v159, v230, s[76:77]
	v_cndmask_b32_e64 v160, v160, v230, s[78:79]
	v_cndmask_b32_e64 v161, v161, v230, s[80:81]
.Ld16a_nma0:
.Ld16a_fj0:
	v_fmamk_f32 v130, v130, 0x3e0293ee, v210
	v_fmamk_f32 v131, v131, 0x3e0293ee, v210
	v_fmamk_f32 v132, v132, 0x3e0293ee, v210
	v_fmamk_f32 v133, v133, 0x3e0293ee, v210
	v_fmamk_f32 v134, v134, 0x3e0293ee, v210
	v_fmamk_f32 v135, v135, 0x3e0293ee, v210
	v_fmamk_f32 v136, v136, 0x3e0293ee, v210
	v_fmamk_f32 v137, v137, 0x3e0293ee, v210
	v_fmamk_f32 v138, v138, 0x3e0293ee, v210
	v_fmamk_f32 v139, v139, 0x3e0293ee, v210
	v_fmamk_f32 v140, v140, 0x3e0293ee, v210
	v_fmamk_f32 v141, v141, 0x3e0293ee, v210
	v_fmamk_f32 v142, v142, 0x3e0293ee, v210
	v_fmamk_f32 v143, v143, 0x3e0293ee, v210
	v_fmamk_f32 v144, v144, 0x3e0293ee, v210
	v_fmamk_f32 v145, v145, 0x3e0293ee, v210
	v_fmamk_f32 v146, v146, 0x3e0293ee, v211
	v_fmamk_f32 v147, v147, 0x3e0293ee, v211
	v_fmamk_f32 v148, v148, 0x3e0293ee, v211
	v_fmamk_f32 v149, v149, 0x3e0293ee, v211
	v_fmamk_f32 v150, v150, 0x3e0293ee, v211
	v_fmamk_f32 v151, v151, 0x3e0293ee, v211
	v_fmamk_f32 v152, v152, 0x3e0293ee, v211
	v_fmamk_f32 v153, v153, 0x3e0293ee, v211
	v_fmamk_f32 v154, v154, 0x3e0293ee, v211
	v_fmamk_f32 v155, v155, 0x3e0293ee, v211
	v_fmamk_f32 v156, v156, 0x3e0293ee, v211
	v_fmamk_f32 v157, v157, 0x3e0293ee, v211
	v_fmamk_f32 v158, v158, 0x3e0293ee, v211
	v_fmamk_f32 v159, v159, 0x3e0293ee, v211
	v_fmamk_f32 v160, v160, 0x3e0293ee, v211
	v_fmamk_f32 v161, v161, 0x3e0293ee, v211
	v_exp_f32_e32 v130, v130
	v_exp_f32_e32 v131, v131
	v_exp_f32_e32 v132, v132
	v_exp_f32_e32 v133, v133
	v_exp_f32_e32 v134, v134
	v_exp_f32_e32 v135, v135
	v_exp_f32_e32 v136, v136
	v_exp_f32_e32 v137, v137
	v_exp_f32_e32 v138, v138
	v_exp_f32_e32 v139, v139
	v_exp_f32_e32 v140, v140
	v_exp_f32_e32 v141, v141
	v_exp_f32_e32 v142, v142
	v_exp_f32_e32 v143, v143
	v_exp_f32_e32 v144, v144
	v_exp_f32_e32 v145, v145
	v_exp_f32_e32 v146, v146
	v_exp_f32_e32 v147, v147
	v_exp_f32_e32 v148, v148
	v_exp_f32_e32 v149, v149
	v_exp_f32_e32 v150, v150
	v_exp_f32_e32 v151, v151
	v_exp_f32_e32 v152, v152
	v_exp_f32_e32 v153, v153
	v_exp_f32_e32 v154, v154
	v_exp_f32_e32 v155, v155
	v_exp_f32_e32 v156, v156
	v_exp_f32_e32 v157, v157
	v_exp_f32_e32 v158, v158
	v_exp_f32_e32 v159, v159
	v_exp_f32_e32 v160, v160
	v_exp_f32_e32 v161, v161
	v_add_f32_e32 v246, v130, v131
	v_add_f32_e32 v247, v146, v147
	v_add_f32_e32 v246, v246, v132
	v_add_f32_e32 v247, v247, v148
	v_add_f32_e32 v246, v246, v133
	v_add_f32_e32 v247, v247, v149
	v_add_f32_e32 v246, v246, v134
	v_add_f32_e32 v247, v247, v150
	v_add_f32_e32 v246, v246, v135
	v_add_f32_e32 v247, v247, v151
	v_add_f32_e32 v246, v246, v136
	v_add_f32_e32 v247, v247, v152
	v_add_f32_e32 v246, v246, v137
	v_add_f32_e32 v247, v247, v153
	v_add_f32_e32 v246, v246, v138
	v_add_f32_e32 v247, v247, v154
	v_add_f32_e32 v246, v246, v139
	v_add_f32_e32 v247, v247, v155
	v_add_f32_e32 v246, v246, v140
	v_add_f32_e32 v247, v247, v156
	v_add_f32_e32 v246, v246, v141
	v_add_f32_e32 v247, v247, v157
	v_add_f32_e32 v246, v246, v142
	v_add_f32_e32 v247, v247, v158
	v_add_f32_e32 v246, v246, v143
	v_add_f32_e32 v247, v247, v159
	v_add_f32_e32 v246, v246, v144
	v_add_f32_e32 v247, v247, v160
	v_add_f32_e32 v246, v246, v145
	v_add_f32_e32 v247, v247, v161
	v_cmp_lt_f32_e32 vcc, s82, v246
	v_cmp_lt_f32_e64 s[74:75], s82, v247
	s_nop 3
	s_or_b64 vcc, vcc, s[74:75]
	s_cbranch_vccnz .Ld16a_rd0
	v_add_f32_e32 v0, v0, v246
	v_add_f32_e32 v223, v223, v247
	v_cvt_pk_bf16_f32 v130, v130, v131
	v_cvt_pk_bf16_f32 v131, v132, v133
	v_cvt_pk_bf16_f32 v132, v134, v135
	v_cvt_pk_bf16_f32 v133, v136, v137
	v_cvt_pk_bf16_f32 v134, v138, v139
	v_cvt_pk_bf16_f32 v135, v140, v141
	v_cvt_pk_bf16_f32 v136, v142, v143
	v_cvt_pk_bf16_f32 v137, v144, v145
	v_cvt_pk_bf16_f32 v138, v146, v147
	v_cvt_pk_bf16_f32 v139, v148, v149
	v_cvt_pk_bf16_f32 v140, v150, v151
	v_cvt_pk_bf16_f32 v141, v152, v153
	v_cvt_pk_bf16_f32 v142, v154, v155
	v_cvt_pk_bf16_f32 v143, v156, v157
	v_cvt_pk_bf16_f32 v144, v158, v159
	v_cvt_pk_bf16_f32 v145, v160, v161
	ds_read_b64_tr_b16 v[146:147], v217 offset:0
	ds_read_b64_tr_b16 v[148:149], v217 offset:8192
	ds_read_b64_tr_b16 v[150:151], v217 offset:16384
	ds_read_b64_tr_b16 v[152:153], v217 offset:24576
	ds_read_b64_tr_b16 v[154:155], v217 offset:256
	ds_read_b64_tr_b16 v[156:157], v217 offset:8448
	ds_read_b64_tr_b16 v[158:159], v217 offset:16640
	ds_read_b64_tr_b16 v[160:161], v217 offset:24832
	s_waitcnt lgkmcnt(6)
	v_mfma_f32_16x16x32_bf16 v[2:5], v[130:133], v[146:149], v[2:5]
	v_mfma_f32_16x16x32_bf16 v[66:69], v[138:141], v[146:149], v[66:69]
	ds_read_b64_tr_b16 v[146:147], v217 offset:512
	ds_read_b64_tr_b16 v[148:149], v217 offset:8704
	s_waitcnt lgkmcnt(6)
	v_mfma_f32_16x16x32_bf16 v[2:5], v[134:137], v[150:153], v[2:5]
	v_mfma_f32_16x16x32_bf16 v[66:69], v[142:145], v[150:153], v[66:69]
	ds_read_b64_tr_b16 v[150:151], v217 offset:16896
	ds_read_b64_tr_b16 v[152:153], v217 offset:25088
	s_waitcnt lgkmcnt(6)
	v_mfma_f32_16x16x32_bf16 v[6:9], v[130:133], v[154:157], v[6:9]
	v_mfma_f32_16x16x32_bf16 v[70:73], v[138:141], v[154:157], v[70:73]
	ds_read_b64_tr_b16 v[154:155], v217 offset:768
	ds_read_b64_tr_b16 v[156:157], v217 offset:8960
	s_waitcnt lgkmcnt(6)
	v_mfma_f32_16x16x32_bf16 v[6:9], v[134:137], v[158:161], v[6:9]
	v_mfma_f32_16x16x32_bf16 v[70:73], v[142:145], v[158:161], v[70:73]
	ds_read_b64_tr_b16 v[158:159], v217 offset:17152
	ds_read_b64_tr_b16 v[160:161], v217 offset:25344
	s_waitcnt lgkmcnt(6)
	v_mfma_f32_16x16x32_bf16 v[10:13], v[130:133], v[146:149], v[10:13]
	v_mfma_f32_16x16x32_bf16 v[74:77], v[138:141], v[146:149], v[74:77]
	ds_read_b64_tr_b16 v[146:147], v217 offset:1024
	ds_read_b64_tr_b16 v[148:149], v217 offset:9216
	s_waitcnt lgkmcnt(6)
	v_mfma_f32_16x16x32_bf16 v[10:13], v[134:137], v[150:153], v[10:13]
	v_mfma_f32_16x16x32_bf16 v[74:77], v[142:145], v[150:153], v[74:77]
	ds_read_b64_tr_b16 v[150:151], v217 offset:17408
	ds_read_b64_tr_b16 v[152:153], v217 offset:25600
	s_waitcnt lgkmcnt(6)
	v_mfma_f32_16x16x32_bf16 v[14:17], v[130:133], v[154:157], v[14:17]
	v_mfma_f32_16x16x32_bf16 v[78:81], v[138:141], v[154:157], v[78:81]
	ds_read_b64_tr_b16 v[154:155], v217 offset:1280
	ds_read_b64_tr_b16 v[156:157], v217 offset:9472
	s_waitcnt lgkmcnt(6)
	v_mfma_f32_16x16x32_bf16 v[14:17], v[134:137], v[158:161], v[14:17]
	v_mfma_f32_16x16x32_bf16 v[78:81], v[142:145], v[158:161], v[78:81]
	ds_read_b64_tr_b16 v[158:159], v217 offset:17664
	ds_read_b64_tr_b16 v[160:161], v217 offset:25856
	s_waitcnt lgkmcnt(6)
	v_mfma_f32_16x16x32_bf16 v[18:21], v[130:133], v[146:149], v[18:21]
	v_mfma_f32_16x16x32_bf16 v[82:85], v[138:141], v[146:149], v[82:85]
	ds_read_b64_tr_b16 v[146:147], v217 offset:1536
	ds_read_b64_tr_b16 v[148:149], v217 offset:9728
	s_waitcnt lgkmcnt(6)
	v_mfma_f32_16x16x32_bf16 v[18:21], v[134:137], v[150:153], v[18:21]
	v_mfma_f32_16x16x32_bf16 v[82:85], v[142:145], v[150:153], v[82:85]
	ds_read_b64_tr_b16 v[150:151], v217 offset:17920
	ds_read_b64_tr_b16 v[152:153], v217 offset:26112
	s_waitcnt lgkmcnt(6)
	v_mfma_f32_16x16x32_bf16 v[22:25], v[130:133], v[154:157], v[22:25]
	v_mfma_f32_16x16x32_bf16 v[86:89], v[138:141], v[154:157], v[86:89]
	ds_read_b64_tr_b16 v[154:155], v217 offset:1792
	ds_read_b64_tr_b16 v[156:157], v217 offset:9984
	s_waitcnt lgkmcnt(6)
	v_mfma_f32_16x16x32_bf16 v[22:25], v[134:137], v[158:161], v[22:25]
	v_mfma_f32_16x16x32_bf16 v[86:89], v[142:145], v[158:161], v[86:89]
	ds_read_b64_tr_b16 v[158:159], v217 offset:18176
	ds_read_b64_tr_b16 v[160:161], v217 offset:26368
	s_waitcnt lgkmcnt(6)
	v_mfma_f32_16x16x32_bf16 v[26:29], v[130:133], v[146:149], v[26:29]
	v_mfma_f32_16x16x32_bf16 v[90:93], v[138:141], v[146:149], v[90:93]
	ds_read_b64_tr_b16 v[146:147], v217 offset:2048
	ds_read_b64_tr_b16 v[148:149], v217 offset:10240
	s_waitcnt lgkmcnt(6)
	v_mfma_f32_16x16x32_bf16 v[26:29], v[134:137], v[150:153], v[26:29]
	v_mfma_f32_16x16x32_bf16 v[90:93], v[142:145], v[150:153], v[90:93]
	ds_read_b64_tr_b16 v[150:151], v217 offset:18432
	ds_read_b64_tr_b16 v[152:153], v217 offset:26624
	s_waitcnt lgkmcnt(6)
	v_mfma_f32_16x16x32_bf16 v[30:33], v[130:133], v[154:157], v[30:33]
	v_mfma_f32_16x16x32_bf16 v[94:97], v[138:141], v[154:157], v[94:97]
	ds_read_b64_tr_b16 v[154:155], v217 offset:2304
	ds_read_b64_tr_b16 v[156:157], v217 offset:10496
	s_waitcnt lgkmcnt(6)
	v_mfma_f32_16x16x32_bf16 v[30:33], v[134:137], v[158:161], v[30:33]
	v_mfma_f32_16x16x32_bf16 v[94:97], v[142:145], v[158:161], v[94:97]
	ds_read_b64_tr_b16 v[158:159], v217 offset:18688
	ds_read_b64_tr_b16 v[160:161], v217 offset:26880
	s_waitcnt lgkmcnt(6)
	v_mfma_f32_16x16x32_bf16 v[34:37], v[130:133], v[146:149], v[34:37]
	v_mfma_f32_16x16x32_bf16 v[98:101], v[138:141], v[146:149], v[98:101]
	ds_read_b64_tr_b16 v[146:147], v217 offset:2560
	ds_read_b64_tr_b16 v[148:149], v217 offset:10752
	s_waitcnt lgkmcnt(6)
	v_mfma_f32_16x16x32_bf16 v[34:37], v[134:137], v[150:153], v[34:37]
	v_mfma_f32_16x16x32_bf16 v[98:101], v[142:145], v[150:153], v[98:101]
	ds_read_b64_tr_b16 v[150:151], v217 offset:18944
	ds_read_b64_tr_b16 v[152:153], v217 offset:27136
	s_waitcnt lgkmcnt(6)
	v_mfma_f32_16x16x32_bf16 v[38:41], v[130:133], v[154:157], v[38:41]
	v_mfma_f32_16x16x32_bf16 v[102:105], v[138:141], v[154:157], v[102:105]
	ds_read_b64_tr_b16 v[154:155], v217 offset:2816
	ds_read_b64_tr_b16 v[156:157], v217 offset:11008
	s_waitcnt lgkmcnt(6)
	v_mfma_f32_16x16x32_bf16 v[38:41], v[134:137], v[158:161], v[38:41]
	v_mfma_f32_16x16x32_bf16 v[102:105], v[142:145], v[158:161], v[102:105]
	ds_read_b64_tr_b16 v[158:159], v217 offset:19200
	ds_read_b64_tr_b16 v[160:161], v217 offset:27392
	s_waitcnt lgkmcnt(6)
	v_mfma_f32_16x16x32_bf16 v[42:45], v[130:133], v[146:149], v[42:45]
	v_mfma_f32_16x16x32_bf16 v[106:109], v[138:141], v[146:149], v[106:109]
	ds_read_b64_tr_b16 v[146:147], v217 offset:3072
	ds_read_b64_tr_b16 v[148:149], v217 offset:11264
	s_waitcnt lgkmcnt(6)
	v_mfma_f32_16x16x32_bf16 v[42:45], v[134:137], v[150:153], v[42:45]
	v_mfma_f32_16x16x32_bf16 v[106:109], v[142:145], v[150:153], v[106:109]
	ds_read_b64_tr_b16 v[150:151], v217 offset:19456
	ds_read_b64_tr_b16 v[152:153], v217 offset:27648
	s_waitcnt lgkmcnt(6)
	v_mfma_f32_16x16x32_bf16 v[46:49], v[130:133], v[154:157], v[46:49]
	v_mfma_f32_16x16x32_bf16 v[110:113], v[138:141], v[154:157], v[110:113]
	ds_read_b64_tr_b16 v[154:155], v217 offset:3328
	ds_read_b64_tr_b16 v[156:157], v217 offset:11520
	s_waitcnt lgkmcnt(6)
	v_mfma_f32_16x16x32_bf16 v[46:49], v[134:137], v[158:161], v[46:49]
	v_mfma_f32_16x16x32_bf16 v[110:113], v[142:145], v[158:161], v[110:113]
	ds_read_b64_tr_b16 v[158:159], v217 offset:19712
	ds_read_b64_tr_b16 v[160:161], v217 offset:27904
	s_waitcnt lgkmcnt(6)
	v_mfma_f32_16x16x32_bf16 v[50:53], v[130:133], v[146:149], v[50:53]
	v_mfma_f32_16x16x32_bf16 v[114:117], v[138:141], v[146:149], v[114:117]
	ds_read_b64_tr_b16 v[146:147], v217 offset:3584
	ds_read_b64_tr_b16 v[148:149], v217 offset:11776
	s_waitcnt lgkmcnt(6)
	v_mfma_f32_16x16x32_bf16 v[50:53], v[134:137], v[150:153], v[50:53]
	v_mfma_f32_16x16x32_bf16 v[114:117], v[142:145], v[150:153], v[114:117]
	ds_read_b64_tr_b16 v[150:151], v217 offset:19968
	ds_read_b64_tr_b16 v[152:153], v217 offset:28160
	s_waitcnt lgkmcnt(6)
	v_mfma_f32_16x16x32_bf16 v[54:57], v[130:133], v[154:157], v[54:57]
	v_mfma_f32_16x16x32_bf16 v[118:121], v[138:141], v[154:157], v[118:121]
	ds_read_b64_tr_b16 v[154:155], v217 offset:3840
	ds_read_b64_tr_b16 v[156:157], v217 offset:12032
	s_waitcnt lgkmcnt(6)
	v_mfma_f32_16x16x32_bf16 v[54:57], v[134:137], v[158:161], v[54:57]
	v_mfma_f32_16x16x32_bf16 v[118:121], v[142:145], v[158:161], v[118:121]
	ds_read_b64_tr_b16 v[158:159], v217 offset:20224
	ds_read_b64_tr_b16 v[160:161], v217 offset:28416
	s_waitcnt lgkmcnt(6)
	v_mfma_f32_16x16x32_bf16 v[58:61], v[130:133], v[146:149], v[58:61]
	v_mfma_f32_16x16x32_bf16 v[122:125], v[138:141], v[146:149], v[122:125]
	s_waitcnt lgkmcnt(4)
	v_mfma_f32_16x16x32_bf16 v[58:61], v[134:137], v[150:153], v[58:61]
	v_mfma_f32_16x16x32_bf16 v[122:125], v[142:145], v[150:153], v[122:125]
	s_waitcnt lgkmcnt(2)
	v_mfma_f32_16x16x32_bf16 v[62:65], v[130:133], v[154:157], v[62:65]
	v_mfma_f32_16x16x32_bf16 v[126:129], v[138:141], v[154:157], v[126:129]
	s_waitcnt lgkmcnt(0)
	v_mfma_f32_16x16x32_bf16 v[62:65], v[134:137], v[158:161], v[62:65]
	v_mfma_f32_16x16x32_bf16 v[126:129], v[142:145], v[158:161], v[126:129]
	s_branch .Ld16a_end0
.Ld16a_rd0:
	ds_read_b128 v[238:241], v218 offset:0
	ds_read_b128 v[242:245], v219 offset:0
	ds_read_b128 v[246:249], v218 offset:128
	ds_read_b128 v[252:255], v219 offset:128
	s_waitcnt lgkmcnt(3)
	v_mfma_f32_16x16x32_bf16 v[130:133], v[238:241], v[162:165], 0
	v_mfma_f32_16x16x32_bf16 v[146:149], v[238:241], v[178:181], 0
	ds_read_b128 v[238:241], v218 offset:4096
	s_waitcnt lgkmcnt(3)
	v_mfma_f32_16x16x32_bf16 v[130:133], v[242:245], v[166:169], v[130:133]
	v_mfma_f32_16x16x32_bf16 v[146:149], v[242:245], v[182:185], v[146:149]
	ds_read_b128 v[242:245], v219 offset:4096
	s_waitcnt lgkmcnt(3)
	v_mfma_f32_16x16x32_bf16 v[130:133], v[246:249], v[170:173], v[130:133]
	v_mfma_f32_16x16x32_bf16 v[146:149], v[246:249], v[186:189], v[146:149]
	ds_read_b128 v[246:249], v218 offset:4224
	s_waitcnt lgkmcnt(3)
	v_mfma_f32_16x16x32_bf16 v[130:133], v[252:255], v[174:177], v[130:133]
	v_mfma_f32_16x16x32_bf16 v[146:149], v[252:255], v[190:193], v[146:149]
	ds_read_b128 v[252:255], v219 offset:4224
	s_waitcnt lgkmcnt(3)
	v_mfma_f32_16x16x32_bf16 v[134:137], v[238:241], v[162:165], 0
	v_mfma_f32_16x16x32_bf16 v[150:153], v[238:241], v[178:181], 0
	ds_read_b128 v[238:241], v218 offset:8192
	s_waitcnt lgkmcnt(3)
	v_mfma_f32_16x16x32_bf16 v[134:137], v[242:245], v[166:169], v[134:137]
	v_mfma_f32_16x16x32_bf16 v[150:153], v[242:245], v[182:185], v[150:153]
	ds_read_b128 v[242:245], v219 offset:8192
	s_waitcnt lgkmcnt(3)
	v_mfma_f32_16x16x32_bf16 v[134:137], v[246:249], v[170:173], v[134:137]
	v_mfma_f32_16x16x32_bf16 v[150:153], v[246:249], v[186:189], v[150:153]
	ds_read_b128 v[246:249], v218 offset:8320
	s_waitcnt lgkmcnt(3)
	v_mfma_f32_16x16x32_bf16 v[134:137], v[252:255], v[174:177], v[134:137]
	v_mfma_f32_16x16x32_bf16 v[150:153], v[252:255], v[190:193], v[150:153]
	ds_read_b128 v[252:255], v219 offset:8320
	s_waitcnt lgkmcnt(3)
	v_mfma_f32_16x16x32_bf16 v[138:141], v[238:241], v[162:165], 0
	v_mfma_f32_16x16x32_bf16 v[154:157], v[238:241], v[178:181], 0
	ds_read_b128 v[238:241], v218 offset:12288
	s_waitcnt lgkmcnt(3)
	v_mfma_f32_16x16x32_bf16 v[138:141], v[242:245], v[166:169], v[138:141]
	v_mfma_f32_16x16x32_bf16 v[154:157], v[242:245], v[182:185], v[154:157]
	ds_read_b128 v[242:245], v219 offset:12288
	s_waitcnt lgkmcnt(3)
	v_mfma_f32_16x16x32_bf16 v[138:141], v[246:249], v[170:173], v[138:141]
	v_mfma_f32_16x16x32_bf16 v[154:157], v[246:249], v[186:189], v[154:157]
	ds_read_b128 v[246:249], v218 offset:12416
	s_waitcnt lgkmcnt(3)
	v_mfma_f32_16x16x32_bf16 v[138:141], v[252:255], v[174:177], v[138:141]
	v_mfma_f32_16x16x32_bf16 v[154:157], v[252:255], v[190:193], v[154:157]
	ds_read_b128 v[252:255], v219 offset:12416
	s_waitcnt lgkmcnt(3)
	v_mfma_f32_16x16x32_bf16 v[142:145], v[238:241], v[162:165], 0
	v_mfma_f32_16x16x32_bf16 v[158:161], v[238:241], v[178:181], 0
	s_waitcnt lgkmcnt(2)
	v_mfma_f32_16x16x32_bf16 v[142:145], v[242:245], v[166:169], v[142:145]
	v_mfma_f32_16x16x32_bf16 v[158:161], v[242:245], v[182:185], v[158:161]
	s_waitcnt lgkmcnt(1)
	v_mfma_f32_16x16x32_bf16 v[142:145], v[246:249], v[170:173], v[142:145]
	v_mfma_f32_16x16x32_bf16 v[158:161], v[246:249], v[186:189], v[158:161]
	s_waitcnt lgkmcnt(0)
	v_mfma_f32_16x16x32_bf16 v[142:145], v[252:255], v[174:177], v[142:145]
	v_mfma_f32_16x16x32_bf16 v[158:161], v[252:255], v[190:193], v[158:161]
	s_nop 7
	s_nop 1
	s_sub_i32 s36, s56, 64
	s_cmp_le_i32 s36, s4
	s_cbranch_scc1 .Ld16a_nmb0
	v_cmp_gt_i32_e64 s[74:75], 0, v233
	v_cmp_gt_i32_e64 s[76:77], 1, v233
	v_cmp_gt_i32_e64 s[78:79], 2, v233
	v_cmp_gt_i32_e64 s[80:81], 3, v233
	v_cndmask_b32_e64 v130, v130, v230, s[74:75]
	v_cndmask_b32_e64 v131, v131, v230, s[76:77]
	v_cndmask_b32_e64 v132, v132, v230, s[78:79]
	v_cndmask_b32_e64 v133, v133, v230, s[80:81]
	v_cmp_gt_i32_e64 s[74:75], 16, v233
	v_cmp_gt_i32_e64 s[76:77], 17, v233
	v_cmp_gt_i32_e64 s[78:79], 18, v233
	v_cmp_gt_i32_e64 s[80:81], 19, v233
	v_cndmask_b32_e64 v134, v134, v230, s[74:75]
	v_cndmask_b32_e64 v135, v135, v230, s[76:77]
	v_cndmask_b32_e64 v136, v136, v230, s[78:79]
	v_cndmask_b32_e64 v137, v137, v230, s[80:81]
	v_cmp_gt_i32_e64 s[74:75], 32, v233
	v_cmp_gt_i32_e64 s[76:77], 33, v233
	v_cmp_gt_i32_e64 s[78:79], 34, v233
	v_cmp_gt_i32_e64 s[80:81], 35, v233
	v_cndmask_b32_e64 v138, v138, v230, s[74:75]
	v_cndmask_b32_e64 v139, v139, v230, s[76:77]
	v_cndmask_b32_e64 v140, v140, v230, s[78:79]
	v_cndmask_b32_e64 v141, v141, v230, s[80:81]
	v_cmp_gt_i32_e64 s[74:75], 48, v233
	v_cmp_gt_i32_e64 s[76:77], 49, v233
	v_cmp_gt_i32_e64 s[78:79], 50, v233
	v_cmp_gt_i32_e64 s[80:81], 51, v233
	v_cndmask_b32_e64 v142, v142, v230, s[74:75]
	v_cndmask_b32_e64 v143, v143, v230, s[76:77]
	v_cndmask_b32_e64 v144, v144, v230, s[78:79]
	v_cndmask_b32_e64 v145, v145, v230, s[80:81]
	v_cmp_gt_i32_e64 s[74:75], -16, v233
	v_cmp_gt_i32_e64 s[76:77], -15, v233
	v_cmp_gt_i32_e64 s[78:79], -14, v233
	v_cmp_gt_i32_e64 s[80:81], -13, v233
	v_cndmask_b32_e64 v146, v146, v230, s[74:75]
	v_cndmask_b32_e64 v147, v147, v230, s[76:77]
	v_cndmask_b32_e64 v148, v148, v230, s[78:79]
	v_cndmask_b32_e64 v149, v149, v230, s[80:81]
	v_cmp_gt_i32_e64 s[74:75], 0, v233
	v_cmp_gt_i32_e64 s[76:77], 1, v233
	v_cmp_gt_i32_e64 s[78:79], 2, v233
	v_cmp_gt_i32_e64 s[80:81], 3, v233
	v_cndmask_b32_e64 v150, v150, v230, s[74:75]
	v_cndmask_b32_e64 v151, v151, v230, s[76:77]
	v_cndmask_b32_e64 v152, v152, v230, s[78:79]
	v_cndmask_b32_e64 v153, v153, v230, s[80:81]
	v_cmp_gt_i32_e64 s[74:75], 16, v233
	v_cmp_gt_i32_e64 s[76:77], 17, v233
	v_cmp_gt_i32_e64 s[78:79], 18, v233
	v_cmp_gt_i32_e64 s[80:81], 19, v233
	v_cndmask_b32_e64 v154, v154, v230, s[74:75]
	v_cndmask_b32_e64 v155, v155, v230, s[76:77]
	v_cndmask_b32_e64 v156, v156, v230, s[78:79]
	v_cndmask_b32_e64 v157, v157, v230, s[80:81]
	v_cmp_gt_i32_e64 s[74:75], 32, v233
	v_cmp_gt_i32_e64 s[76:77], 33, v233
	v_cmp_gt_i32_e64 s[78:79], 34, v233
	v_cmp_gt_i32_e64 s[80:81], 35, v233
	v_cndmask_b32_e64 v158, v158, v230, s[74:75]
	v_cndmask_b32_e64 v159, v159, v230, s[76:77]
	v_cndmask_b32_e64 v160, v160, v230, s[78:79]
	v_cndmask_b32_e64 v161, v161, v230, s[80:81]
.Ld16a_nmb0:
	v_max3_f32 v234, v130, v131, v132
	v_max3_f32 v234, v234, v133, v134
	v_max3_f32 v234, v234, v135, v136
	v_max3_f32 v234, v234, v137, v138
	v_max3_f32 v234, v234, v139, v140
	v_max3_f32 v234, v234, v141, v142
	v_max3_f32 v234, v234, v143, v144
	v_max_f32_e32 v234, v234, v145
	v_max3_f32 v235, v146, v147, v148
	v_max3_f32 v235, v235, v149, v150
	v_max3_f32 v235, v235, v151, v152
	v_max3_f32 v235, v235, v153, v154
	v_max3_f32 v235, v235, v155, v156
	v_max3_f32 v235, v235, v157, v158
	v_max3_f32 v235, v235, v159, v160
	v_max_f32_e32 v235, v235, v161
	v_mov_b32_e32 v246, v234
	v_mov_b32_e32 v247, v235
	s_nop 1
	v_permlane16_swap_b32_e32 v234, v246
	v_permlane16_swap_b32_e32 v235, v247
	v_max_f32_e32 v234, v234, v246
	v_max_f32_e32 v235, v235, v247
	v_mov_b32_e32 v246, v234
	v_mov_b32_e32 v247, v235
	s_nop 1
	v_permlane32_swap_b32_e32 v234, v246
	v_permlane32_swap_b32_e32 v235, v247
	v_max_f32_e32 v234, v234, v246
	v_max_f32_e32 v235, v235, v247
	v_max_f32_e32 v234, v237, v234
	v_max_f32_e32 v235, v222, v235
	v_sub_f32_e32 v246, v237, v234
	v_sub_f32_e32 v247, v222, v235
	v_mul_f32_e32 v246, 0x3e0293ee, v246
	v_mul_f32_e32 v247, 0x3e0293ee, v247
	v_exp_f32_e32 v246, v246
	v_exp_f32_e32 v247, v247
	v_mov_b32_e32 v237, v234
	v_mov_b32_e32 v222, v235
	v_mul_f32_e32 v210, 0xbe0293ee, v234
	v_mul_f32_e32 v211, 0xbe0293ee, v235
	v_mul_f32_e32 v0, v0, v246
	v_mul_f32_e32 v223, v223, v247
	s_and_saveexec_b64 s[76:77], s[0:1]
	ds_write_b32 v232, v246 offset:128
	ds_write_b32 v232, v247 offset:192
	s_or_b64 exec, exec, s[76:77]
	s_waitcnt lgkmcnt(0)
	ds_read_b128 v[238:241], v231 offset:128
	ds_read_b128 v[242:245], v231 offset:192
	s_waitcnt lgkmcnt(0)
	v_pk_mul_f32 v[2:3], v[2:3], v[238:239]
	v_pk_mul_f32 v[4:5], v[4:5], v[240:241]
	v_pk_mul_f32 v[6:7], v[6:7], v[238:239]
	v_pk_mul_f32 v[8:9], v[8:9], v[240:241]
	v_pk_mul_f32 v[10:11], v[10:11], v[238:239]
	v_pk_mul_f32 v[12:13], v[12:13], v[240:241]
	v_pk_mul_f32 v[14:15], v[14:15], v[238:239]
	v_pk_mul_f32 v[16:17], v[16:17], v[240:241]
	v_pk_mul_f32 v[18:19], v[18:19], v[238:239]
	v_pk_mul_f32 v[20:21], v[20:21], v[240:241]
	v_pk_mul_f32 v[22:23], v[22:23], v[238:239]
	v_pk_mul_f32 v[24:25], v[24:25], v[240:241]
	v_pk_mul_f32 v[26:27], v[26:27], v[238:239]
	v_pk_mul_f32 v[28:29], v[28:29], v[240:241]
	v_pk_mul_f32 v[30:31], v[30:31], v[238:239]
	v_pk_mul_f32 v[32:33], v[32:33], v[240:241]
	v_pk_mul_f32 v[34:35], v[34:35], v[238:239]
	v_pk_mul_f32 v[36:37], v[36:37], v[240:241]
	v_pk_mul_f32 v[38:39], v[38:39], v[238:239]
	v_pk_mul_f32 v[40:41], v[40:41], v[240:241]
	v_pk_mul_f32 v[42:43], v[42:43], v[238:239]
	v_pk_mul_f32 v[44:45], v[44:45], v[240:241]
	v_pk_mul_f32 v[46:47], v[46:47], v[238:239]
	v_pk_mul_f32 v[48:49], v[48:49], v[240:241]
	v_pk_mul_f32 v[50:51], v[50:51], v[238:239]
	v_pk_mul_f32 v[52:53], v[52:53], v[240:241]
	v_pk_mul_f32 v[54:55], v[54:55], v[238:239]
	v_pk_mul_f32 v[56:57], v[56:57], v[240:241]
	v_pk_mul_f32 v[58:59], v[58:59], v[238:239]
	v_pk_mul_f32 v[60:61], v[60:61], v[240:241]
	v_pk_mul_f32 v[62:63], v[62:63], v[238:239]
	v_pk_mul_f32 v[64:65], v[64:65], v[240:241]
	v_pk_mul_f32 v[66:67], v[66:67], v[242:243]
	v_pk_mul_f32 v[68:69], v[68:69], v[244:245]
	v_pk_mul_f32 v[70:71], v[70:71], v[242:243]
	v_pk_mul_f32 v[72:73], v[72:73], v[244:245]
	v_pk_mul_f32 v[74:75], v[74:75], v[242:243]
	v_pk_mul_f32 v[76:77], v[76:77], v[244:245]
	v_pk_mul_f32 v[78:79], v[78:79], v[242:243]
	v_pk_mul_f32 v[80:81], v[80:81], v[244:245]
	v_pk_mul_f32 v[82:83], v[82:83], v[242:243]
	v_pk_mul_f32 v[84:85], v[84:85], v[244:245]
	v_pk_mul_f32 v[86:87], v[86:87], v[242:243]
	v_pk_mul_f32 v[88:89], v[88:89], v[244:245]
	v_pk_mul_f32 v[90:91], v[90:91], v[242:243]
	v_pk_mul_f32 v[92:93], v[92:93], v[244:245]
	v_pk_mul_f32 v[94:95], v[94:95], v[242:243]
	v_pk_mul_f32 v[96:97], v[96:97], v[244:245]
	v_pk_mul_f32 v[98:99], v[98:99], v[242:243]
	v_pk_mul_f32 v[100:101], v[100:101], v[244:245]
	v_pk_mul_f32 v[102:103], v[102:103], v[242:243]
	v_pk_mul_f32 v[104:105], v[104:105], v[244:245]
	v_pk_mul_f32 v[106:107], v[106:107], v[242:243]
	v_pk_mul_f32 v[108:109], v[108:109], v[244:245]
	v_pk_mul_f32 v[110:111], v[110:111], v[242:243]
	v_pk_mul_f32 v[112:113], v[112:113], v[244:245]
	v_pk_mul_f32 v[114:115], v[114:115], v[242:243]
	v_pk_mul_f32 v[116:117], v[116:117], v[244:245]
	v_pk_mul_f32 v[118:119], v[118:119], v[242:243]
	v_pk_mul_f32 v[120:121], v[120:121], v[244:245]
	v_pk_mul_f32 v[122:123], v[122:123], v[242:243]
	v_pk_mul_f32 v[124:125], v[124:125], v[244:245]
	v_pk_mul_f32 v[126:127], v[126:127], v[242:243]
	v_pk_mul_f32 v[128:129], v[128:129], v[244:245]
	s_branch .Ld16a_fj0

.Ld16a_nma1:
.Ld16a_fj1:
	v_fmamk_f32 v130, v130, 0x3e0293ee, v210
	v_fmamk_f32 v131, v131, 0x3e0293ee, v210
	v_fmamk_f32 v132, v132, 0x3e0293ee, v210
	v_fmamk_f32 v133, v133, 0x3e0293ee, v210
	v_fmamk_f32 v134, v134, 0x3e0293ee, v210
	v_fmamk_f32 v135, v135, 0x3e0293ee, v210
	v_fmamk_f32 v136, v136, 0x3e0293ee, v210
	v_fmamk_f32 v137, v137, 0x3e0293ee, v210
	v_fmamk_f32 v138, v138, 0x3e0293ee, v210
	v_fmamk_f32 v139, v139, 0x3e0293ee, v210
	v_fmamk_f32 v140, v140, 0x3e0293ee, v210
	v_fmamk_f32 v141, v141, 0x3e0293ee, v210
	v_fmamk_f32 v142, v142, 0x3e0293ee, v210
	v_fmamk_f32 v143, v143, 0x3e0293ee, v210
	v_fmamk_f32 v144, v144, 0x3e0293ee, v210
	v_fmamk_f32 v145, v145, 0x3e0293ee, v210
	v_fmamk_f32 v146, v146, 0x3e0293ee, v211
	v_fmamk_f32 v147, v147, 0x3e0293ee, v211
	v_fmamk_f32 v148, v148, 0x3e0293ee, v211
	v_fmamk_f32 v149, v149, 0x3e0293ee, v211
	v_fmamk_f32 v150, v150, 0x3e0293ee, v211
	v_fmamk_f32 v151, v151, 0x3e0293ee, v211
	v_fmamk_f32 v152, v152, 0x3e0293ee, v211
	v_fmamk_f32 v153, v153, 0x3e0293ee, v211
	v_fmamk_f32 v154, v154, 0x3e0293ee, v211
	v_fmamk_f32 v155, v155, 0x3e0293ee, v211
	v_fmamk_f32 v156, v156, 0x3e0293ee, v211
	v_fmamk_f32 v157, v157, 0x3e0293ee, v211
	v_fmamk_f32 v158, v158, 0x3e0293ee, v211
	v_fmamk_f32 v159, v159, 0x3e0293ee, v211
	v_fmamk_f32 v160, v160, 0x3e0293ee, v211
	v_fmamk_f32 v161, v161, 0x3e0293ee, v211
	v_exp_f32_e32 v130, v130
	v_exp_f32_e32 v131, v131
	v_exp_f32_e32 v132, v132
	v_exp_f32_e32 v133, v133
	v_exp_f32_e32 v134, v134
	v_exp_f32_e32 v135, v135
	v_exp_f32_e32 v136, v136
	v_exp_f32_e32 v137, v137
	v_exp_f32_e32 v138, v138
	v_exp_f32_e32 v139, v139
	v_exp_f32_e32 v140, v140
	v_exp_f32_e32 v141, v141
	v_exp_f32_e32 v142, v142
	v_exp_f32_e32 v143, v143
	v_exp_f32_e32 v144, v144
	v_exp_f32_e32 v145, v145
	v_exp_f32_e32 v146, v146
	v_exp_f32_e32 v147, v147
	v_exp_f32_e32 v148, v148
	v_exp_f32_e32 v149, v149
	v_exp_f32_e32 v150, v150
	v_exp_f32_e32 v151, v151
	v_exp_f32_e32 v152, v152
	v_exp_f32_e32 v153, v153
	v_exp_f32_e32 v154, v154
	v_exp_f32_e32 v155, v155
	v_exp_f32_e32 v156, v156
	v_exp_f32_e32 v157, v157
	v_exp_f32_e32 v158, v158
	v_exp_f32_e32 v159, v159
	v_exp_f32_e32 v160, v160
	v_exp_f32_e32 v161, v161
	v_add_f32_e32 v246, v130, v131
	v_add_f32_e32 v247, v146, v147
	v_add_f32_e32 v246, v246, v132
	v_add_f32_e32 v247, v247, v148
	v_add_f32_e32 v246, v246, v133
	v_add_f32_e32 v247, v247, v149
	v_add_f32_e32 v246, v246, v134
	v_add_f32_e32 v247, v247, v150
	v_add_f32_e32 v246, v246, v135
	v_add_f32_e32 v247, v247, v151
	v_add_f32_e32 v246, v246, v136
	v_add_f32_e32 v247, v247, v152
	v_add_f32_e32 v246, v246, v137
	v_add_f32_e32 v247, v247, v153
	v_add_f32_e32 v246, v246, v138
	v_add_f32_e32 v247, v247, v154
	v_add_f32_e32 v246, v246, v139
	v_add_f32_e32 v247, v247, v155
	v_add_f32_e32 v246, v246, v140
	v_add_f32_e32 v247, v247, v156
	v_add_f32_e32 v246, v246, v141
	v_add_f32_e32 v247, v247, v157
	v_add_f32_e32 v246, v246, v142
	v_add_f32_e32 v247, v247, v158
	v_add_f32_e32 v246, v246, v143
	v_add_f32_e32 v247, v247, v159
	v_add_f32_e32 v246, v246, v144
	v_add_f32_e32 v247, v247, v160
	v_add_f32_e32 v246, v246, v145
	v_add_f32_e32 v247, v247, v161
	v_cmp_lt_f32_e32 vcc, s82, v246
	v_cmp_lt_f32_e64 s[74:75], s82, v247
	s_nop 3
	s_or_b64 vcc, vcc, s[74:75]
	s_cbranch_vccnz .Ld16a_rd1
	v_add_f32_e32 v0, v0, v246
	v_add_f32_e32 v223, v223, v247
	v_cvt_pk_bf16_f32 v130, v130, v131
	v_cvt_pk_bf16_f32 v131, v132, v133
	v_cvt_pk_bf16_f32 v132, v134, v135
	v_cvt_pk_bf16_f32 v133, v136, v137
	v_cvt_pk_bf16_f32 v134, v138, v139
	v_cvt_pk_bf16_f32 v135, v140, v141
	v_cvt_pk_bf16_f32 v136, v142, v143
	v_cvt_pk_bf16_f32 v137, v144, v145
	v_cvt_pk_bf16_f32 v138, v146, v147
	v_cvt_pk_bf16_f32 v139, v148, v149
	v_cvt_pk_bf16_f32 v140, v150, v151
	v_cvt_pk_bf16_f32 v141, v152, v153
	v_cvt_pk_bf16_f32 v142, v154, v155
	v_cvt_pk_bf16_f32 v143, v156, v157
	v_cvt_pk_bf16_f32 v144, v158, v159
	v_cvt_pk_bf16_f32 v145, v160, v161
	ds_read_b64_tr_b16 v[146:147], v217 offset:32768
	ds_read_b64_tr_b16 v[148:149], v217 offset:40960
	ds_read_b64_tr_b16 v[150:151], v217 offset:49152
	ds_read_b64_tr_b16 v[152:153], v217 offset:57344
	ds_read_b64_tr_b16 v[154:155], v217 offset:33024
	ds_read_b64_tr_b16 v[156:157], v217 offset:41216
	ds_read_b64_tr_b16 v[158:159], v217 offset:49408
	ds_read_b64_tr_b16 v[160:161], v217 offset:57600
	s_waitcnt lgkmcnt(6)
	v_mfma_f32_16x16x32_bf16 v[2:5], v[130:133], v[146:149], v[2:5]
	v_mfma_f32_16x16x32_bf16 v[66:69], v[138:141], v[146:149], v[66:69]
	ds_read_b64_tr_b16 v[146:147], v217 offset:33280
	ds_read_b64_tr_b16 v[148:149], v217 offset:41472
	s_waitcnt lgkmcnt(6)
	v_mfma_f32_16x16x32_bf16 v[2:5], v[134:137], v[150:153], v[2:5]
	v_mfma_f32_16x16x32_bf16 v[66:69], v[142:145], v[150:153], v[66:69]
	ds_read_b64_tr_b16 v[150:151], v217 offset:49664
	ds_read_b64_tr_b16 v[152:153], v217 offset:57856
	s_waitcnt lgkmcnt(6)
	v_mfma_f32_16x16x32_bf16 v[6:9], v[130:133], v[154:157], v[6:9]
	v_mfma_f32_16x16x32_bf16 v[70:73], v[138:141], v[154:157], v[70:73]
	ds_read_b64_tr_b16 v[154:155], v217 offset:33536
	ds_read_b64_tr_b16 v[156:157], v217 offset:41728
	s_waitcnt lgkmcnt(6)
	v_mfma_f32_16x16x32_bf16 v[6:9], v[134:137], v[158:161], v[6:9]
	v_mfma_f32_16x16x32_bf16 v[70:73], v[142:145], v[158:161], v[70:73]
	ds_read_b64_tr_b16 v[158:159], v217 offset:49920
	ds_read_b64_tr_b16 v[160:161], v217 offset:58112
	s_waitcnt lgkmcnt(6)
	v_mfma_f32_16x16x32_bf16 v[10:13], v[130:133], v[146:149], v[10:13]
	v_mfma_f32_16x16x32_bf16 v[74:77], v[138:141], v[146:149], v[74:77]
	ds_read_b64_tr_b16 v[146:147], v217 offset:33792
	ds_read_b64_tr_b16 v[148:149], v217 offset:41984
	s_waitcnt lgkmcnt(6)
	v_mfma_f32_16x16x32_bf16 v[10:13], v[134:137], v[150:153], v[10:13]
	v_mfma_f32_16x16x32_bf16 v[74:77], v[142:145], v[150:153], v[74:77]
	ds_read_b64_tr_b16 v[150:151], v217 offset:50176
	ds_read_b64_tr_b16 v[152:153], v217 offset:58368
	s_waitcnt lgkmcnt(6)
	v_mfma_f32_16x16x32_bf16 v[14:17], v[130:133], v[154:157], v[14:17]
	v_mfma_f32_16x16x32_bf16 v[78:81], v[138:141], v[154:157], v[78:81]
	ds_read_b64_tr_b16 v[154:155], v217 offset:34048
	ds_read_b64_tr_b16 v[156:157], v217 offset:42240
	s_waitcnt lgkmcnt(6)
	v_mfma_f32_16x16x32_bf16 v[14:17], v[134:137], v[158:161], v[14:17]
	v_mfma_f32_16x16x32_bf16 v[78:81], v[142:145], v[158:161], v[78:81]
	ds_read_b64_tr_b16 v[158:159], v217 offset:50432
	ds_read_b64_tr_b16 v[160:161], v217 offset:58624
	s_waitcnt lgkmcnt(6)
	v_mfma_f32_16x16x32_bf16 v[18:21], v[130:133], v[146:149], v[18:21]
	v_mfma_f32_16x16x32_bf16 v[82:85], v[138:141], v[146:149], v[82:85]
	ds_read_b64_tr_b16 v[146:147], v217 offset:34304
	ds_read_b64_tr_b16 v[148:149], v217 offset:42496
	s_waitcnt lgkmcnt(6)
	v_mfma_f32_16x16x32_bf16 v[18:21], v[134:137], v[150:153], v[18:21]
	v_mfma_f32_16x16x32_bf16 v[82:85], v[142:145], v[150:153], v[82:85]
	ds_read_b64_tr_b16 v[150:151], v217 offset:50688
	ds_read_b64_tr_b16 v[152:153], v217 offset:58880
	s_waitcnt lgkmcnt(6)
	v_mfma_f32_16x16x32_bf16 v[22:25], v[130:133], v[154:157], v[22:25]
	v_mfma_f32_16x16x32_bf16 v[86:89], v[138:141], v[154:157], v[86:89]
	ds_read_b64_tr_b16 v[154:155], v217 offset:34560
	ds_read_b64_tr_b16 v[156:157], v217 offset:42752
	s_waitcnt lgkmcnt(6)
	v_mfma_f32_16x16x32_bf16 v[22:25], v[134:137], v[158:161], v[22:25]
	v_mfma_f32_16x16x32_bf16 v[86:89], v[142:145], v[158:161], v[86:89]
	ds_read_b64_tr_b16 v[158:159], v217 offset:50944
	ds_read_b64_tr_b16 v[160:161], v217 offset:59136
	s_waitcnt lgkmcnt(6)
	v_mfma_f32_16x16x32_bf16 v[26:29], v[130:133], v[146:149], v[26:29]
	v_mfma_f32_16x16x32_bf16 v[90:93], v[138:141], v[146:149], v[90:93]
	ds_read_b64_tr_b16 v[146:147], v217 offset:34816
	ds_read_b64_tr_b16 v[148:149], v217 offset:43008
	s_waitcnt lgkmcnt(6)
	v_mfma_f32_16x16x32_bf16 v[26:29], v[134:137], v[150:153], v[26:29]
	v_mfma_f32_16x16x32_bf16 v[90:93], v[142:145], v[150:153], v[90:93]
	ds_read_b64_tr_b16 v[150:151], v217 offset:51200
	ds_read_b64_tr_b16 v[152:153], v217 offset:59392
	s_waitcnt lgkmcnt(6)
	v_mfma_f32_16x16x32_bf16 v[30:33], v[130:133], v[154:157], v[30:33]
	v_mfma_f32_16x16x32_bf16 v[94:97], v[138:141], v[154:157], v[94:97]
	ds_read_b64_tr_b16 v[154:155], v217 offset:35072
	ds_read_b64_tr_b16 v[156:157], v217 offset:43264
	s_waitcnt lgkmcnt(6)
	v_mfma_f32_16x16x32_bf16 v[30:33], v[134:137], v[158:161], v[30:33]
	v_mfma_f32_16x16x32_bf16 v[94:97], v[142:145], v[158:161], v[94:97]
	ds_read_b64_tr_b16 v[158:159], v217 offset:51456
	ds_read_b64_tr_b16 v[160:161], v217 offset:59648
	s_waitcnt lgkmcnt(6)
	v_mfma_f32_16x16x32_bf16 v[34:37], v[130:133], v[146:149], v[34:37]
	v_mfma_f32_16x16x32_bf16 v[98:101], v[138:141], v[146:149], v[98:101]
	ds_read_b64_tr_b16 v[146:147], v217 offset:35328
	ds_read_b64_tr_b16 v[148:149], v217 offset:43520
	s_waitcnt lgkmcnt(6)
	v_mfma_f32_16x16x32_bf16 v[34:37], v[134:137], v[150:153], v[34:37]
	v_mfma_f32_16x16x32_bf16 v[98:101], v[142:145], v[150:153], v[98:101]
	ds_read_b64_tr_b16 v[150:151], v217 offset:51712
	ds_read_b64_tr_b16 v[152:153], v217 offset:59904
	s_waitcnt lgkmcnt(6)
	v_mfma_f32_16x16x32_bf16 v[38:41], v[130:133], v[154:157], v[38:41]
	v_mfma_f32_16x16x32_bf16 v[102:105], v[138:141], v[154:157], v[102:105]
	ds_read_b64_tr_b16 v[154:155], v217 offset:35584
	ds_read_b64_tr_b16 v[156:157], v217 offset:43776
	s_waitcnt lgkmcnt(6)
	v_mfma_f32_16x16x32_bf16 v[38:41], v[134:137], v[158:161], v[38:41]
	v_mfma_f32_16x16x32_bf16 v[102:105], v[142:145], v[158:161], v[102:105]
	ds_read_b64_tr_b16 v[158:159], v217 offset:51968
	ds_read_b64_tr_b16 v[160:161], v217 offset:60160
	s_waitcnt lgkmcnt(6)
	v_mfma_f32_16x16x32_bf16 v[42:45], v[130:133], v[146:149], v[42:45]
	v_mfma_f32_16x16x32_bf16 v[106:109], v[138:141], v[146:149], v[106:109]
	ds_read_b64_tr_b16 v[146:147], v217 offset:35840
	ds_read_b64_tr_b16 v[148:149], v217 offset:44032
	s_waitcnt lgkmcnt(6)
	v_mfma_f32_16x16x32_bf16 v[42:45], v[134:137], v[150:153], v[42:45]
	v_mfma_f32_16x16x32_bf16 v[106:109], v[142:145], v[150:153], v[106:109]
	ds_read_b64_tr_b16 v[150:151], v217 offset:52224
	ds_read_b64_tr_b16 v[152:153], v217 offset:60416
	s_waitcnt lgkmcnt(6)
	v_mfma_f32_16x16x32_bf16 v[46:49], v[130:133], v[154:157], v[46:49]
	v_mfma_f32_16x16x32_bf16 v[110:113], v[138:141], v[154:157], v[110:113]
	ds_read_b64_tr_b16 v[154:155], v217 offset:36096
	ds_read_b64_tr_b16 v[156:157], v217 offset:44288
	s_waitcnt lgkmcnt(6)
	v_mfma_f32_16x16x32_bf16 v[46:49], v[134:137], v[158:161], v[46:49]
	v_mfma_f32_16x16x32_bf16 v[110:113], v[142:145], v[158:161], v[110:113]
	ds_read_b64_tr_b16 v[158:159], v217 offset:52480
	ds_read_b64_tr_b16 v[160:161], v217 offset:60672
	s_waitcnt lgkmcnt(6)
	v_mfma_f32_16x16x32_bf16 v[50:53], v[130:133], v[146:149], v[50:53]
	v_mfma_f32_16x16x32_bf16 v[114:117], v[138:141], v[146:149], v[114:117]
	ds_read_b64_tr_b16 v[146:147], v217 offset:36352
	ds_read_b64_tr_b16 v[148:149], v217 offset:44544
	s_waitcnt lgkmcnt(6)
	v_mfma_f32_16x16x32_bf16 v[50:53], v[134:137], v[150:153], v[50:53]
	v_mfma_f32_16x16x32_bf16 v[114:117], v[142:145], v[150:153], v[114:117]
	ds_read_b64_tr_b16 v[150:151], v217 offset:52736
	ds_read_b64_tr_b16 v[152:153], v217 offset:60928
	s_waitcnt lgkmcnt(6)
	v_mfma_f32_16x16x32_bf16 v[54:57], v[130:133], v[154:157], v[54:57]
	v_mfma_f32_16x16x32_bf16 v[118:121], v[138:141], v[154:157], v[118:121]
	ds_read_b64_tr_b16 v[154:155], v217 offset:36608
	ds_read_b64_tr_b16 v[156:157], v217 offset:44800
	s_waitcnt lgkmcnt(6)
	v_mfma_f32_16x16x32_bf16 v[54:57], v[134:137], v[158:161], v[54:57]
	v_mfma_f32_16x16x32_bf16 v[118:121], v[142:145], v[158:161], v[118:121]
	ds_read_b64_tr_b16 v[158:159], v217 offset:52992
	ds_read_b64_tr_b16 v[160:161], v217 offset:61184
	s_waitcnt lgkmcnt(6)
	v_mfma_f32_16x16x32_bf16 v[58:61], v[130:133], v[146:149], v[58:61]
	v_mfma_f32_16x16x32_bf16 v[122:125], v[138:141], v[146:149], v[122:125]
	s_waitcnt lgkmcnt(4)
	v_mfma_f32_16x16x32_bf16 v[58:61], v[134:137], v[150:153], v[58:61]
	v_mfma_f32_16x16x32_bf16 v[122:125], v[142:145], v[150:153], v[122:125]
	s_waitcnt lgkmcnt(2)
	v_mfma_f32_16x16x32_bf16 v[62:65], v[130:133], v[154:157], v[62:65]
	v_mfma_f32_16x16x32_bf16 v[126:129], v[138:141], v[154:157], v[126:129]
	s_waitcnt lgkmcnt(0)
	v_mfma_f32_16x16x32_bf16 v[62:65], v[134:137], v[158:161], v[62:65]
	v_mfma_f32_16x16x32_bf16 v[126:129], v[142:145], v[158:161], v[126:129]
	s_branch .Ld16a_end1
.Ld16a_rd1:
	ds_read_b128 v[238:241], v218 offset:16384
	ds_read_b128 v[242:245], v219 offset:16384
	ds_read_b128 v[246:249], v218 offset:16512
	ds_read_b128 v[252:255], v219 offset:16512
	s_waitcnt lgkmcnt(3)
	v_mfma_f32_16x16x32_bf16 v[130:133], v[238:241], v[162:165], 0
	v_mfma_f32_16x16x32_bf16 v[146:149], v[238:241], v[178:181], 0
	ds_read_b128 v[238:241], v218 offset:20480
	s_waitcnt lgkmcnt(3)
	v_mfma_f32_16x16x32_bf16 v[130:133], v[242:245], v[166:169], v[130:133]
	v_mfma_f32_16x16x32_bf16 v[146:149], v[242:245], v[182:185], v[146:149]
	ds_read_b128 v[242:245], v219 offset:20480
	s_waitcnt lgkmcnt(3)
	v_mfma_f32_16x16x32_bf16 v[130:133], v[246:249], v[170:173], v[130:133]
	v_mfma_f32_16x16x32_bf16 v[146:149], v[246:249], v[186:189], v[146:149]
	ds_read_b128 v[246:249], v218 offset:20608
	s_waitcnt lgkmcnt(3)
	v_mfma_f32_16x16x32_bf16 v[130:133], v[252:255], v[174:177], v[130:133]
	v_mfma_f32_16x16x32_bf16 v[146:149], v[252:255], v[190:193], v[146:149]
	ds_read_b128 v[252:255], v219 offset:20608
	s_waitcnt lgkmcnt(3)
	v_mfma_f32_16x16x32_bf16 v[134:137], v[238:241], v[162:165], 0
	v_mfma_f32_16x16x32_bf16 v[150:153], v[238:241], v[178:181], 0
	ds_read_b128 v[238:241], v218 offset:24576
	s_waitcnt lgkmcnt(3)
	v_mfma_f32_16x16x32_bf16 v[134:137], v[242:245], v[166:169], v[134:137]
	v_mfma_f32_16x16x32_bf16 v[150:153], v[242:245], v[182:185], v[150:153]
	ds_read_b128 v[242:245], v219 offset:24576
	s_waitcnt lgkmcnt(3)
	v_mfma_f32_16x16x32_bf16 v[134:137], v[246:249], v[170:173], v[134:137]
	v_mfma_f32_16x16x32_bf16 v[150:153], v[246:249], v[186:189], v[150:153]
	ds_read_b128 v[246:249], v218 offset:24704
	s_waitcnt lgkmcnt(3)
	v_mfma_f32_16x16x32_bf16 v[134:137], v[252:255], v[174:177], v[134:137]
	v_mfma_f32_16x16x32_bf16 v[150:153], v[252:255], v[190:193], v[150:153]
	ds_read_b128 v[252:255], v219 offset:24704
	s_waitcnt lgkmcnt(3)
	v_mfma_f32_16x16x32_bf16 v[138:141], v[238:241], v[162:165], 0
	v_mfma_f32_16x16x32_bf16 v[154:157], v[238:241], v[178:181], 0
	ds_read_b128 v[238:241], v218 offset:28672
	s_waitcnt lgkmcnt(3)
	v_mfma_f32_16x16x32_bf16 v[138:141], v[242:245], v[166:169], v[138:141]
	v_mfma_f32_16x16x32_bf16 v[154:157], v[242:245], v[182:185], v[154:157]
	ds_read_b128 v[242:245], v219 offset:28672
	s_waitcnt lgkmcnt(3)
	v_mfma_f32_16x16x32_bf16 v[138:141], v[246:249], v[170:173], v[138:141]
	v_mfma_f32_16x16x32_bf16 v[154:157], v[246:249], v[186:189], v[154:157]
	ds_read_b128 v[246:249], v218 offset:28800
	s_waitcnt lgkmcnt(3)
	v_mfma_f32_16x16x32_bf16 v[138:141], v[252:255], v[174:177], v[138:141]
	v_mfma_f32_16x16x32_bf16 v[154:157], v[252:255], v[190:193], v[154:157]
	ds_read_b128 v[252:255], v219 offset:28800
	s_waitcnt lgkmcnt(3)
	v_mfma_f32_16x16x32_bf16 v[142:145], v[238:241], v[162:165], 0
	v_mfma_f32_16x16x32_bf16 v[158:161], v[238:241], v[178:181], 0
	s_waitcnt lgkmcnt(2)
	v_mfma_f32_16x16x32_bf16 v[142:145], v[242:245], v[166:169], v[142:145]
	v_mfma_f32_16x16x32_bf16 v[158:161], v[242:245], v[182:185], v[158:161]
	s_waitcnt lgkmcnt(1)
	v_mfma_f32_16x16x32_bf16 v[142:145], v[246:249], v[170:173], v[142:145]
	v_mfma_f32_16x16x32_bf16 v[158:161], v[246:249], v[186:189], v[158:161]
	s_waitcnt lgkmcnt(0)
	v_mfma_f32_16x16x32_bf16 v[142:145], v[252:255], v[174:177], v[142:145]
	v_mfma_f32_16x16x32_bf16 v[158:161], v[252:255], v[190:193], v[158:161]
	s_nop 7
	s_nop 1
	s_cmp_le_i32 s56, s4
	s_cbranch_scc1 .Ld16a_nmb1
	v_subrev_u32_e32 v246, 64, v233
	v_cmp_gt_i32_e64 s[74:75], 0, v246
	v_cmp_gt_i32_e64 s[76:77], 1, v246
	v_cmp_gt_i32_e64 s[78:79], 2, v246
	v_cmp_gt_i32_e64 s[80:81], 3, v246
	v_cndmask_b32_e64 v130, v130, v230, s[74:75]
	v_cndmask_b32_e64 v131, v131, v230, s[76:77]
	v_cndmask_b32_e64 v132, v132, v230, s[78:79]
	v_cndmask_b32_e64 v133, v133, v230, s[80:81]
	v_cmp_gt_i32_e64 s[74:75], 16, v246
	v_cmp_gt_i32_e64 s[76:77], 17, v246
	v_cmp_gt_i32_e64 s[78:79], 18, v246
	v_cmp_gt_i32_e64 s[80:81], 19, v246
	v_cndmask_b32_e64 v134, v134, v230, s[74:75]
	v_cndmask_b32_e64 v135, v135, v230, s[76:77]
	v_cndmask_b32_e64 v136, v136, v230, s[78:79]
	v_cndmask_b32_e64 v137, v137, v230, s[80:81]
	v_cmp_gt_i32_e64 s[74:75], 32, v246
	v_cmp_gt_i32_e64 s[76:77], 33, v246
	v_cmp_gt_i32_e64 s[78:79], 34, v246
	v_cmp_gt_i32_e64 s[80:81], 35, v246
	v_cndmask_b32_e64 v138, v138, v230, s[74:75]
	v_cndmask_b32_e64 v139, v139, v230, s[76:77]
	v_cndmask_b32_e64 v140, v140, v230, s[78:79]
	v_cndmask_b32_e64 v141, v141, v230, s[80:81]
	v_cmp_gt_i32_e64 s[74:75], 48, v246
	v_cmp_gt_i32_e64 s[76:77], 49, v246
	v_cmp_gt_i32_e64 s[78:79], 50, v246
	v_cmp_gt_i32_e64 s[80:81], 51, v246
	v_cndmask_b32_e64 v142, v142, v230, s[74:75]
	v_cndmask_b32_e64 v143, v143, v230, s[76:77]
	v_cndmask_b32_e64 v144, v144, v230, s[78:79]
	v_cndmask_b32_e64 v145, v145, v230, s[80:81]
	v_cmp_gt_i32_e64 s[74:75], -16, v246
	v_cmp_gt_i32_e64 s[76:77], -15, v246
	v_cmp_gt_i32_e64 s[78:79], -14, v246
	v_cmp_gt_i32_e64 s[80:81], -13, v246
	v_cndmask_b32_e64 v146, v146, v230, s[74:75]
	v_cndmask_b32_e64 v147, v147, v230, s[76:77]
	v_cndmask_b32_e64 v148, v148, v230, s[78:79]
	v_cndmask_b32_e64 v149, v149, v230, s[80:81]
	v_cmp_gt_i32_e64 s[74:75], 0, v246
	v_cmp_gt_i32_e64 s[76:77], 1, v246
	v_cmp_gt_i32_e64 s[78:79], 2, v246
	v_cmp_gt_i32_e64 s[80:81], 3, v246
	v_cndmask_b32_e64 v150, v150, v230, s[74:75]
	v_cndmask_b32_e64 v151, v151, v230, s[76:77]
	v_cndmask_b32_e64 v152, v152, v230, s[78:79]
	v_cndmask_b32_e64 v153, v153, v230, s[80:81]
	v_cmp_gt_i32_e64 s[74:75], 16, v246
	v_cmp_gt_i32_e64 s[76:77], 17, v246
	v_cmp_gt_i32_e64 s[78:79], 18, v246
	v_cmp_gt_i32_e64 s[80:81], 19, v246
	v_cndmask_b32_e64 v154, v154, v230, s[74:75]
	v_cndmask_b32_e64 v155, v155, v230, s[76:77]
	v_cndmask_b32_e64 v156, v156, v230, s[78:79]
	v_cndmask_b32_e64 v157, v157, v230, s[80:81]
	v_cmp_gt_i32_e64 s[74:75], 32, v246
	v_cmp_gt_i32_e64 s[76:77], 33, v246
	v_cmp_gt_i32_e64 s[78:79], 34, v246
	v_cmp_gt_i32_e64 s[80:81], 35, v246
	v_cndmask_b32_e64 v158, v158, v230, s[74:75]
	v_cndmask_b32_e64 v159, v159, v230, s[76:77]
	v_cndmask_b32_e64 v160, v160, v230, s[78:79]
	v_cndmask_b32_e64 v161, v161, v230, s[80:81]

.LBB0_2403:
	v_readlane_b32 s10, v251, 42
	s_add_u32 s0, s48, s10
	v_readlane_b32 s4, v251, 43
	s_addc_u32 s1, s49, s4
	s_add_u32 s44, s0, 0x2000
	v_readlane_b32 s2, v251, 38
	s_addc_u32 s45, s1, 0
	s_lshl_b32 s2, s2, 1
	s_add_u32 s0, s0, s2
	s_addc_u32 s1, s1, 0
	s_add_u32 s8, s0, 0x2800
	v_readlane_b32 s0, v251, 8
	s_addc_u32 s9, s1, 0
	v_mbcnt_lo_u32_b32 v0, -1, 0
	v_mbcnt_hi_u32_b32 v0, -1, v0
	v_readlane_b32 s2, v251, 40
	v_add_u32_e32 v208, s0, v0
	s_mov_b64 s[0:1], s[68:69]
	s_load_dwordx2 s[0:1], s[0:1], 0x88
	s_lshl_b32 s2, s2, 1
	v_and_b32_e32 v2, 63, v0
	v_lshlrev_b32_e32 v5, 4, v0
	s_waitcnt lgkmcnt(0)
	v_lshlrev_b32_e32 v4, 3, v2
	s_add_u32 s0, s0, s2
	v_and_b32_e32 v6, 0xc0, v5
	v_lshlrev_b32_e32 v7, 1, v0
	s_addc_u32 s1, s1, 0
	v_and_or_b32 v6, v4, 24, v6
	v_and_b32_e32 v7, 32, v7
	v_and_b32_e32 v4, 0x100, v4
	v_bfe_u32 v212, v0, 4, 2
	s_add_u32 s46, s0, 0x37e00000
	v_bfe_u32 v1, v0, 5, 1
	v_or3_b32 v4, v6, v7, v4
	v_bitop3_b32 v7, v212, v0, 15 bitop3:0x78
	s_addc_u32 s47, s1, 0
	v_lshlrev_b32_e32 v210, 2, v1
	v_lshlrev_b32_e32 v213, 4, v7
	v_lshlrev_b32_e32 v7, 4, v1
	v_lshrrev_b32_e32 v1, 1, v0
	v_and_b32_e32 v209, 31, v0
	v_and_b32_e32 v215, 8, v1
	v_lshlrev_b32_e32 v1, 3, v0
	s_cmp_lg_u32 0, -1
	v_mul_u32_u24_e32 v3, 0x3000, v209
	v_and_b32_e32 v1, 24, v1
	s_cselect_b32 s2, 0, 0
	s_movk_i32 s0, 0x70
	v_and_b32_e32 v6, 15, v0
	v_or_b32_e32 v194, v7, v3
	v_bfe_u32 v214, v0, 2, 3
	v_and_or_b32 v216, v0, 32, v1
	v_add_u32_e32 v217, s2, v4
	v_lshlrev_b32_e32 v0, 8, v209
	v_and_b32_e32 v3, 0x70, v5
	s_add_i32 s1, s2, 0x10000
	v_bitop3_b32 v5, v7, v5, s0 bitop3:0x78
	s_movk_i32 s0, 0x60
	s_add_i32 s2, s2, 0x14000
	v_add_u32_e32 v4, s1, v0
	v_bitop3_b32 v8, v7, v3, 32 bitop3:0x36
	v_bitop3_b32 v9, v7, v3, 64 bitop3:0x36
	v_bitop3_b32 v3, v7, v3, s0 bitop3:0x36
	v_add_u32_e32 v0, s2, v0
	v_add_u32_e32 v222, v5, v0
	v_add_u32_e32 v223, v8, v0
	v_add_u32_e32 v224, v9, v0
	v_add_u32_e32 v225, v3, v0
	v_mul_u32_u24_e32 v0, 0x3000, v212
	s_movk_i32 s50, 0x3000
	v_mov_b32_e32 v1, 0
	v_cmp_gt_u32_e64 s[0:1], 32, v2
	s_add_u32 s6, s6, s10
	v_mov_b32_e32 v2, 0xc000
	v_or_b32_e32 v227, v0, v213
	v_bitop3_b32 v0, v212, v6, 4 bitop3:0x36
	v_sub_u32_e32 v211, v209, v210
	v_mov_b32_e32 v195, v1
	s_mov_b32 s51, 0
	v_add_u32_e32 v218, v5, v4
	v_add_u32_e32 v219, v8, v4
	v_add_u32_e32 v220, v9, v4
	v_add_u32_e32 v221, v3, v4
	s_addc_u32 s7, s7, s4
	v_mad_u32_u24 v226, v212, s50, v2
	v_lshlrev_b32_e32 v228, 4, v0
	v_mov_b32_e32 v229, 0x7ffffff3
	s_movk_i32 s52, 0x1800
	s_mov_b64 s[10:11], 0x100
	s_mov_b64 s[12:13], 0x180
	s_mov_b64 s[14:15], 0x1fec2000
	s_mov_b64 s[16:17], 0x1fec2800
	s_mov_b64 s[18:19], 0x1fec2880
	s_mov_b64 s[20:21], 0x1fec2900
	s_mov_b64 s[22:23], 0x1fec2980
	s_brev_b32 s53, -3
	s_mov_b32 s54, 0x41000000
	s_mov_b64 s[24:25], 0x1ff82000
	s_mov_b64 s[26:27], 0x1ff82800
	s_mov_b64 s[28:29], 0x1ff82880
	s_mov_b64 s[30:31], 0x1ff82900
	s_mov_b64 s[34:35], 0x1ff82980
	s_mov_b32 s55, 0x7fffe000
	v_mov_b32_e32 v230, 0xff800000
	s_waitcnt vmcnt(63) expcnt(7) lgkmcnt(15)
	v_mbcnt_lo_u32_b32 v238, -1, 0
	v_mbcnt_hi_u32_b32 v238, -1, v238
	v_and_b32_e32 v239, 15, v238
	v_lshrrev_b32_e32 v240, 4, v238
	v_and_b32_e32 v241, 3, v238
	v_bfe_u32 v242, v238, 2, 2
	v_lshrrev_b32_e32 v243, 1, v240
	v_lshlrev_b32_e32 v217, 12, v243
	v_and_b32_e32 v243, 1, v240
	v_lshl_or_b32 v217, v243, 7, v217
	v_lshl_or_b32 v217, v242, 5, v217
	v_lshl_or_b32 v217, v241, 3, v217
	v_xor_b32_e32 v243, v240, v241
	v_lshlrev_b32_e32 v218, 8, v239
	v_lshl_or_b32 v218, v243, 4, v218
	v_bfe_u32 v243, v238, 2, 1
	v_lshl_or_b32 v218, v243, 6, v218
	v_or_b32_e32 v218, 0x10000, v218
	v_xor_b32_e32 v219, 64, v218
	v_bfe_u32 v243, v238, 1, 3
	v_mul_u32_u24_e32 v220, 0x3000, v243
	v_lshl_or_b32 v220, v240, 5, v220
	v_and_b32_e32 v243, 1, v238
	v_lshl_or_b32 v220, v243, 4, v220
	v_lshlrev_b32_e32 v243, 2, v240
	v_sub_u32_e32 v221, v239, v243
	v_mul_u32_u24_e32 v194, 0x3000, v239
	v_lshl_or_b32 v194, v240, 4, v194
	v_add_u32_e32 v194, 0x1800, v194
	v_mov_b32_e32 v195, 0
	v_xor_b32_e32 v224, 16, v238
	v_lshlrev_b32_e32 v224, 2, v224
	v_cmp_gt_u32_e64 s[0:1], 16, v238
	s_mov_b32 s82, 0x453a4f54
	s_barrier
	v_readlane_b32 s3, v251, 41
	s_branch .LBB0_2405

.LBB0_2410:
	s_sub_i32 s73, s60, 158
	s_cmp_gt_i32 s73, s4
	s_cbranch_scc1 .Ld16c_end0
	s_cmp_eq_u32 s61, 2
	s_cbranch_scc1 .Ld16c_rd0
	ds_read_b128 v[252:255], v219 offset:128
	s_waitcnt lgkmcnt(3)
	v_mfma_f32_16x16x32_bf16 v[130:133], v[238:241], v[162:165], 0
	v_mfma_f32_16x16x32_bf16 v[146:149], v[238:241], v[178:181], 0
	ds_read_b128 v[238:241], v218 offset:4096
	s_waitcnt lgkmcnt(3)
	v_mfma_f32_16x16x32_bf16 v[130:133], v[242:245], v[166:169], v[130:133]
	v_mfma_f32_16x16x32_bf16 v[146:149], v[242:245], v[182:185], v[146:149]
	ds_read_b128 v[242:245], v219 offset:4096
	s_waitcnt lgkmcnt(3)
	v_mfma_f32_16x16x32_bf16 v[130:133], v[246:249], v[170:173], v[130:133]
	v_mfma_f32_16x16x32_bf16 v[146:149], v[246:249], v[186:189], v[146:149]
	ds_read_b128 v[246:249], v218 offset:4224
	s_waitcnt lgkmcnt(3)
	v_mfma_f32_16x16x32_bf16 v[130:133], v[252:255], v[174:177], v[130:133]
	v_mfma_f32_16x16x32_bf16 v[146:149], v[252:255], v[190:193], v[146:149]
	ds_read_b128 v[252:255], v219 offset:4224
	s_waitcnt lgkmcnt(3)
	v_mfma_f32_16x16x32_bf16 v[134:137], v[238:241], v[162:165], 0
	v_mfma_f32_16x16x32_bf16 v[150:153], v[238:241], v[178:181], 0
	ds_read_b128 v[238:241], v218 offset:8192
	s_waitcnt lgkmcnt(3)
	v_mfma_f32_16x16x32_bf16 v[134:137], v[242:245], v[166:169], v[134:137]
	v_mfma_f32_16x16x32_bf16 v[150:153], v[242:245], v[182:185], v[150:153]
	ds_read_b128 v[242:245], v219 offset:8192
	s_waitcnt lgkmcnt(3)
	v_mfma_f32_16x16x32_bf16 v[134:137], v[246:249], v[170:173], v[134:137]
	v_mfma_f32_16x16x32_bf16 v[150:153], v[246:249], v[186:189], v[150:153]
	ds_read_b128 v[246:249], v218 offset:8320
	s_waitcnt lgkmcnt(3)
	v_mfma_f32_16x16x32_bf16 v[134:137], v[252:255], v[174:177], v[134:137]
	v_mfma_f32_16x16x32_bf16 v[150:153], v[252:255], v[190:193], v[150:153]
	ds_read_b128 v[252:255], v219 offset:8320
	s_waitcnt lgkmcnt(3)
	v_mfma_f32_16x16x32_bf16 v[138:141], v[238:241], v[162:165], 0
	v_mfma_f32_16x16x32_bf16 v[154:157], v[238:241], v[178:181], 0
	ds_read_b128 v[238:241], v218 offset:12288
	s_waitcnt lgkmcnt(3)
	v_mfma_f32_16x16x32_bf16 v[138:141], v[242:245], v[166:169], v[138:141]
	v_mfma_f32_16x16x32_bf16 v[154:157], v[242:245], v[182:185], v[154:157]
	ds_read_b128 v[242:245], v219 offset:12288
	s_waitcnt lgkmcnt(3)
	v_mfma_f32_16x16x32_bf16 v[138:141], v[246:249], v[170:173], v[138:141]
	v_mfma_f32_16x16x32_bf16 v[154:157], v[246:249], v[186:189], v[154:157]
	ds_read_b128 v[246:249], v218 offset:12416
	s_waitcnt lgkmcnt(3)
	v_mfma_f32_16x16x32_bf16 v[138:141], v[252:255], v[174:177], v[138:141]
	v_mfma_f32_16x16x32_bf16 v[154:157], v[252:255], v[190:193], v[154:157]
	ds_read_b128 v[252:255], v219 offset:12416
	s_waitcnt lgkmcnt(3)
	v_mfma_f32_16x16x32_bf16 v[142:145], v[238:241], v[162:165], 0
	v_mfma_f32_16x16x32_bf16 v[158:161], v[238:241], v[178:181], 0
	s_waitcnt lgkmcnt(2)
	v_mfma_f32_16x16x32_bf16 v[142:145], v[242:245], v[166:169], v[142:145]
	v_mfma_f32_16x16x32_bf16 v[158:161], v[242:245], v[182:185], v[158:161]
	s_waitcnt lgkmcnt(1)
	v_mfma_f32_16x16x32_bf16 v[142:145], v[246:249], v[170:173], v[142:145]
	v_mfma_f32_16x16x32_bf16 v[158:161], v[246:249], v[186:189], v[158:161]
	s_waitcnt lgkmcnt(0)
	v_mfma_f32_16x16x32_bf16 v[142:145], v[252:255], v[174:177], v[142:145]
	v_mfma_f32_16x16x32_bf16 v[158:161], v[252:255], v[190:193], v[158:161]
	s_nop 7
	s_nop 1
	s_sub_i32 s40, s60, 64
	s_cmp_le_i32 s40, s4
	s_cbranch_scc1 .Ld16c_nma0
	v_cmp_gt_i32_e64 s[74:75], 0, v233
	v_cmp_gt_i32_e64 s[76:77], 1, v233
	v_cmp_gt_i32_e64 s[78:79], 2, v233
	v_cmp_gt_i32_e64 s[80:81], 3, v233
	v_cndmask_b32_e64 v130, v130, v230, s[74:75]
	v_cndmask_b32_e64 v131, v131, v230, s[76:77]
	v_cndmask_b32_e64 v132, v132, v230, s[78:79]
	v_cndmask_b32_e64 v133, v133, v230, s[80:81]
	v_cmp_gt_i32_e64 s[74:75], 16, v233
	v_cmp_gt_i32_e64 s[76:77], 17, v233
	v_cmp_gt_i32_e64 s[78:79], 18, v233
	v_cmp_gt_i32_e64 s[80:81], 19, v233
	v_cndmask_b32_e64 v134, v134, v230, s[74:75]
	v_cndmask_b32_e64 v135, v135, v230, s[76:77]
	v_cndmask_b32_e64 v136, v136, v230, s[78:79]
	v_cndmask_b32_e64 v137, v137, v230, s[80:81]
	v_cmp_gt_i32_e64 s[74:75], 32, v233
	v_cmp_gt_i32_e64 s[76:77], 33, v233
	v_cmp_gt_i32_e64 s[78:79], 34, v233
	v_cmp_gt_i32_e64 s[80:81], 35, v233
	v_cndmask_b32_e64 v138, v138, v230, s[74:75]
	v_cndmask_b32_e64 v139, v139, v230, s[76:77]
	v_cndmask_b32_e64 v140, v140, v230, s[78:79]
	v_cndmask_b32_e64 v141, v141, v230, s[80:81]
	v_cmp_gt_i32_e64 s[74:75], 48, v233
	v_cmp_gt_i32_e64 s[76:77], 49, v233
	v_cmp_gt_i32_e64 s[78:79], 50, v233
	v_cmp_gt_i32_e64 s[80:81], 51, v233
	v_cndmask_b32_e64 v142, v142, v230, s[74:75]
	v_cndmask_b32_e64 v143, v143, v230, s[76:77]
	v_cndmask_b32_e64 v144, v144, v230, s[78:79]
	v_cndmask_b32_e64 v145, v145, v230, s[80:81]
	v_cmp_gt_i32_e64 s[74:75], -16, v233
	v_cmp_gt_i32_e64 s[76:77], -15, v233
	v_cmp_gt_i32_e64 s[78:79], -14, v233
	v_cmp_gt_i32_e64 s[80:81], -13, v233
	v_cndmask_b32_e64 v146, v146, v230, s[74:75]
	v_cndmask_b32_e64 v147, v147, v230, s[76:77]
	v_cndmask_b32_e64 v148, v148, v230, s[78:79]
	v_cndmask_b32_e64 v149, v149, v230, s[80:81]
	v_cmp_gt_i32_e64 s[74:75], 0, v233
	v_cmp_gt_i32_e64 s[76:77], 1, v233
	v_cmp_gt_i32_e64 s[78:79], 2, v233
	v_cmp_gt_i32_e64 s[80:81], 3, v233
	v_cndmask_b32_e64 v150, v150, v230, s[74:75]
	v_cndmask_b32_e64 v151, v151, v230, s[76:77]
	v_cndmask_b32_e64 v152, v152, v230, s[78:79]
	v_cndmask_b32_e64 v153, v153, v230, s[80:81]
	v_cmp_gt_i32_e64 s[74:75], 16, v233
	v_cmp_gt_i32_e64 s[76:77], 17, v233
	v_cmp_gt_i32_e64 s[78:79], 18, v233
	v_cmp_gt_i32_e64 s[80:81], 19, v233
	v_cndmask_b32_e64 v154, v154, v230, s[74:75]
	v_cndmask_b32_e64 v155, v155, v230, s[76:77]
	v_cndmask_b32_e64 v156, v156, v230, s[78:79]
	v_cndmask_b32_e64 v157, v157, v230, s[80:81]
	v_cmp_gt_i32_e64 s[74:75], 32, v233
	v_cmp_gt_i32_e64 s[76:77], 33, v233
	v_cmp_gt_i32_e64 s[78:79], 34, v233
	v_cmp_gt_i32_e64 s[80:81], 35, v233
	v_cndmask_b32_e64 v158, v158, v230, s[74:75]
	v_cndmask_b32_e64 v159, v159, v230, s[76:77]
	v_cndmask_b32_e64 v160, v160, v230, s[78:79]
	v_cndmask_b32_e64 v161, v161, v230, s[80:81]

.Ld16c_rd0:
	ds_read_b128 v[238:241], v218 offset:0
	ds_read_b128 v[242:245], v219 offset:0
	ds_read_b128 v[246:249], v218 offset:128
	ds_read_b128 v[252:255], v219 offset:128
	s_waitcnt lgkmcnt(3)
	v_mfma_f32_16x16x32_bf16 v[130:133], v[238:241], v[162:165], 0
	v_mfma_f32_16x16x32_bf16 v[146:149], v[238:241], v[178:181], 0
	ds_read_b128 v[238:241], v218 offset:4096
	s_waitcnt lgkmcnt(3)
	v_mfma_f32_16x16x32_bf16 v[130:133], v[242:245], v[166:169], v[130:133]
	v_mfma_f32_16x16x32_bf16 v[146:149], v[242:245], v[182:185], v[146:149]
	ds_read_b128 v[242:245], v219 offset:4096
	s_waitcnt lgkmcnt(3)
	v_mfma_f32_16x16x32_bf16 v[130:133], v[246:249], v[170:173], v[130:133]
	v_mfma_f32_16x16x32_bf16 v[146:149], v[246:249], v[186:189], v[146:149]
	ds_read_b128 v[246:249], v218 offset:4224
	s_waitcnt lgkmcnt(3)
	v_mfma_f32_16x16x32_bf16 v[130:133], v[252:255], v[174:177], v[130:133]
	v_mfma_f32_16x16x32_bf16 v[146:149], v[252:255], v[190:193], v[146:149]
	ds_read_b128 v[252:255], v219 offset:4224
	s_waitcnt lgkmcnt(3)
	v_mfma_f32_16x16x32_bf16 v[134:137], v[238:241], v[162:165], 0
	v_mfma_f32_16x16x32_bf16 v[150:153], v[238:241], v[178:181], 0
	ds_read_b128 v[238:241], v218 offset:8192
	s_waitcnt lgkmcnt(3)
	v_mfma_f32_16x16x32_bf16 v[134:137], v[242:245], v[166:169], v[134:137]
	v_mfma_f32_16x16x32_bf16 v[150:153], v[242:245], v[182:185], v[150:153]
	ds_read_b128 v[242:245], v219 offset:8192
	s_waitcnt lgkmcnt(3)
	v_mfma_f32_16x16x32_bf16 v[134:137], v[246:249], v[170:173], v[134:137]
	v_mfma_f32_16x16x32_bf16 v[150:153], v[246:249], v[186:189], v[150:153]
	ds_read_b128 v[246:249], v218 offset:8320
	s_waitcnt lgkmcnt(3)
	v_mfma_f32_16x16x32_bf16 v[134:137], v[252:255], v[174:177], v[134:137]
	v_mfma_f32_16x16x32_bf16 v[150:153], v[252:255], v[190:193], v[150:153]
	ds_read_b128 v[252:255], v219 offset:8320
	s_waitcnt lgkmcnt(3)
	v_mfma_f32_16x16x32_bf16 v[138:141], v[238:241], v[162:165], 0
	v_mfma_f32_16x16x32_bf16 v[154:157], v[238:241], v[178:181], 0
	ds_read_b128 v[238:241], v218 offset:12288
	s_waitcnt lgkmcnt(3)
	v_mfma_f32_16x16x32_bf16 v[138:141], v[242:245], v[166:169], v[138:141]
	v_mfma_f32_16x16x32_bf16 v[154:157], v[242:245], v[182:185], v[154:157]
	ds_read_b128 v[242:245], v219 offset:12288
	s_waitcnt lgkmcnt(3)
	v_mfma_f32_16x16x32_bf16 v[138:141], v[246:249], v[170:173], v[138:141]
	v_mfma_f32_16x16x32_bf16 v[154:157], v[246:249], v[186:189], v[154:157]
	ds_read_b128 v[246:249], v218 offset:12416
	s_waitcnt lgkmcnt(3)
	v_mfma_f32_16x16x32_bf16 v[138:141], v[252:255], v[174:177], v[138:141]
	v_mfma_f32_16x16x32_bf16 v[154:157], v[252:255], v[190:193], v[154:157]
	ds_read_b128 v[252:255], v219 offset:12416
	s_waitcnt lgkmcnt(3)
	v_mfma_f32_16x16x32_bf16 v[142:145], v[238:241], v[162:165], 0
	v_mfma_f32_16x16x32_bf16 v[158:161], v[238:241], v[178:181], 0
	s_waitcnt lgkmcnt(2)
	v_mfma_f32_16x16x32_bf16 v[142:145], v[242:245], v[166:169], v[142:145]
	v_mfma_f32_16x16x32_bf16 v[158:161], v[242:245], v[182:185], v[158:161]
	s_waitcnt lgkmcnt(1)
	v_mfma_f32_16x16x32_bf16 v[142:145], v[246:249], v[170:173], v[142:145]
	v_mfma_f32_16x16x32_bf16 v[158:161], v[246:249], v[186:189], v[158:161]
	s_waitcnt lgkmcnt(0)
	v_mfma_f32_16x16x32_bf16 v[142:145], v[252:255], v[174:177], v[142:145]
	v_mfma_f32_16x16x32_bf16 v[158:161], v[252:255], v[190:193], v[158:161]
	s_nop 7
	s_nop 1
	s_sub_i32 s40, s60, 64
	s_cmp_le_i32 s40, s4
	s_cbranch_scc1 .Ld16c_nmb0
	v_cmp_gt_i32_e64 s[74:75], 0, v233
	v_cmp_gt_i32_e64 s[76:77], 1, v233
	v_cmp_gt_i32_e64 s[78:79], 2, v233
	v_cmp_gt_i32_e64 s[80:81], 3, v233
	v_cndmask_b32_e64 v130, v130, v230, s[74:75]
	v_cndmask_b32_e64 v131, v131, v230, s[76:77]
	v_cndmask_b32_e64 v132, v132, v230, s[78:79]
	v_cndmask_b32_e64 v133, v133, v230, s[80:81]
	v_cmp_gt_i32_e64 s[74:75], 16, v233
	v_cmp_gt_i32_e64 s[76:77], 17, v233
	v_cmp_gt_i32_e64 s[78:79], 18, v233
	v_cmp_gt_i32_e64 s[80:81], 19, v233
	v_cndmask_b32_e64 v134, v134, v230, s[74:75]
	v_cndmask_b32_e64 v135, v135, v230, s[76:77]
	v_cndmask_b32_e64 v136, v136, v230, s[78:79]
	v_cndmask_b32_e64 v137, v137, v230, s[80:81]
	v_cmp_gt_i32_e64 s[74:75], 32, v233
	v_cmp_gt_i32_e64 s[76:77], 33, v233
	v_cmp_gt_i32_e64 s[78:79], 34, v233
	v_cmp_gt_i32_e64 s[80:81], 35, v233
	v_cndmask_b32_e64 v138, v138, v230, s[74:75]
	v_cndmask_b32_e64 v139, v139, v230, s[76:77]
	v_cndmask_b32_e64 v140, v140, v230, s[78:79]
	v_cndmask_b32_e64 v141, v141, v230, s[80:81]
	v_cmp_gt_i32_e64 s[74:75], 48, v233
	v_cmp_gt_i32_e64 s[76:77], 49, v233
	v_cmp_gt_i32_e64 s[78:79], 50, v233
	v_cmp_gt_i32_e64 s[80:81], 51, v233
	v_cndmask_b32_e64 v142, v142, v230, s[74:75]
	v_cndmask_b32_e64 v143, v143, v230, s[76:77]
	v_cndmask_b32_e64 v144, v144, v230, s[78:79]
	v_cndmask_b32_e64 v145, v145, v230, s[80:81]
	v_cmp_gt_i32_e64 s[74:75], -16, v233
	v_cmp_gt_i32_e64 s[76:77], -15, v233
	v_cmp_gt_i32_e64 s[78:79], -14, v233
	v_cmp_gt_i32_e64 s[80:81], -13, v233
	v_cndmask_b32_e64 v146, v146, v230, s[74:75]
	v_cndmask_b32_e64 v147, v147, v230, s[76:77]
	v_cndmask_b32_e64 v148, v148, v230, s[78:79]
	v_cndmask_b32_e64 v149, v149, v230, s[80:81]
	v_cmp_gt_i32_e64 s[74:75], 0, v233
	v_cmp_gt_i32_e64 s[76:77], 1, v233
	v_cmp_gt_i32_e64 s[78:79], 2, v233
	v_cmp_gt_i32_e64 s[80:81], 3, v233
	v_cndmask_b32_e64 v150, v150, v230, s[74:75]
	v_cndmask_b32_e64 v151, v151, v230, s[76:77]
	v_cndmask_b32_e64 v152, v152, v230, s[78:79]
	v_cndmask_b32_e64 v153, v153, v230, s[80:81]
	v_cmp_gt_i32_e64 s[74:75], 16, v233
	v_cmp_gt_i32_e64 s[76:77], 17, v233
	v_cmp_gt_i32_e64 s[78:79], 18, v233
	v_cmp_gt_i32_e64 s[80:81], 19, v233
	v_cndmask_b32_e64 v154, v154, v230, s[74:75]
	v_cndmask_b32_e64 v155, v155, v230, s[76:77]
	v_cndmask_b32_e64 v156, v156, v230, s[78:79]
	v_cndmask_b32_e64 v157, v157, v230, s[80:81]
	v_cmp_gt_i32_e64 s[74:75], 32, v233
	v_cmp_gt_i32_e64 s[76:77], 33, v233
	v_cmp_gt_i32_e64 s[78:79], 34, v233
	v_cmp_gt_i32_e64 s[80:81], 35, v233
	v_cndmask_b32_e64 v158, v158, v230, s[74:75]
	v_cndmask_b32_e64 v159, v159, v230, s[76:77]
	v_cndmask_b32_e64 v160, v160, v230, s[78:79]
	v_cndmask_b32_e64 v161, v161, v230, s[80:81]

.Ld16c_rd1:
	ds_read_b128 v[238:241], v218 offset:16384
	ds_read_b128 v[242:245], v219 offset:16384
	ds_read_b128 v[246:249], v218 offset:16512
	ds_read_b128 v[252:255], v219 offset:16512
	s_waitcnt lgkmcnt(3)
	v_mfma_f32_16x16x32_bf16 v[130:133], v[238:241], v[162:165], 0
	v_mfma_f32_16x16x32_bf16 v[146:149], v[238:241], v[178:181], 0
	ds_read_b128 v[238:241], v218 offset:20480
	s_waitcnt lgkmcnt(3)
	v_mfma_f32_16x16x32_bf16 v[130:133], v[242:245], v[166:169], v[130:133]
	v_mfma_f32_16x16x32_bf16 v[146:149], v[242:245], v[182:185], v[146:149]
	ds_read_b128 v[242:245], v219 offset:20480
	s_waitcnt lgkmcnt(3)
	v_mfma_f32_16x16x32_bf16 v[130:133], v[246:249], v[170:173], v[130:133]
	v_mfma_f32_16x16x32_bf16 v[146:149], v[246:249], v[186:189], v[146:149]
	ds_read_b128 v[246:249], v218 offset:20608
	s_waitcnt lgkmcnt(3)
	v_mfma_f32_16x16x32_bf16 v[130:133], v[252:255], v[174:177], v[130:133]
	v_mfma_f32_16x16x32_bf16 v[146:149], v[252:255], v[190:193], v[146:149]
	ds_read_b128 v[252:255], v219 offset:20608
	s_waitcnt lgkmcnt(3)
	v_mfma_f32_16x16x32_bf16 v[134:137], v[238:241], v[162:165], 0
	v_mfma_f32_16x16x32_bf16 v[150:153], v[238:241], v[178:181], 0
	ds_read_b128 v[238:241], v218 offset:24576
	s_waitcnt lgkmcnt(3)
	v_mfma_f32_16x16x32_bf16 v[134:137], v[242:245], v[166:169], v[134:137]
	v_mfma_f32_16x16x32_bf16 v[150:153], v[242:245], v[182:185], v[150:153]
	ds_read_b128 v[242:245], v219 offset:24576
	s_waitcnt lgkmcnt(3)
	v_mfma_f32_16x16x32_bf16 v[134:137], v[246:249], v[170:173], v[134:137]
	v_mfma_f32_16x16x32_bf16 v[150:153], v[246:249], v[186:189], v[150:153]
	ds_read_b128 v[246:249], v218 offset:24704
	s_waitcnt lgkmcnt(3)
	v_mfma_f32_16x16x32_bf16 v[134:137], v[252:255], v[174:177], v[134:137]
	v_mfma_f32_16x16x32_bf16 v[150:153], v[252:255], v[190:193], v[150:153]
	ds_read_b128 v[252:255], v219 offset:24704
	s_waitcnt lgkmcnt(3)
	v_mfma_f32_16x16x32_bf16 v[138:141], v[238:241], v[162:165], 0
	v_mfma_f32_16x16x32_bf16 v[154:157], v[238:241], v[178:181], 0
	ds_read_b128 v[238:241], v218 offset:28672
	s_waitcnt lgkmcnt(3)
	v_mfma_f32_16x16x32_bf16 v[138:141], v[242:245], v[166:169], v[138:141]
	v_mfma_f32_16x16x32_bf16 v[154:157], v[242:245], v[182:185], v[154:157]
	ds_read_b128 v[242:245], v219 offset:28672
	s_waitcnt lgkmcnt(3)
	v_mfma_f32_16x16x32_bf16 v[138:141], v[246:249], v[170:173], v[138:141]
	v_mfma_f32_16x16x32_bf16 v[154:157], v[246:249], v[186:189], v[154:157]
	ds_read_b128 v[246:249], v218 offset:28800
	s_waitcnt lgkmcnt(3)
	v_mfma_f32_16x16x32_bf16 v[138:141], v[252:255], v[174:177], v[138:141]
	v_mfma_f32_16x16x32_bf16 v[154:157], v[252:255], v[190:193], v[154:157]
	ds_read_b128 v[252:255], v219 offset:28800
	s_waitcnt lgkmcnt(3)
	v_mfma_f32_16x16x32_bf16 v[142:145], v[238:241], v[162:165], 0
	v_mfma_f32_16x16x32_bf16 v[158:161], v[238:241], v[178:181], 0
	s_waitcnt lgkmcnt(2)
	v_mfma_f32_16x16x32_bf16 v[142:145], v[242:245], v[166:169], v[142:145]
	v_mfma_f32_16x16x32_bf16 v[158:161], v[242:245], v[182:185], v[158:161]
	s_waitcnt lgkmcnt(1)
	v_mfma_f32_16x16x32_bf16 v[142:145], v[246:249], v[170:173], v[142:145]
	v_mfma_f32_16x16x32_bf16 v[158:161], v[246:249], v[186:189], v[158:161]
	s_waitcnt lgkmcnt(0)
	v_mfma_f32_16x16x32_bf16 v[142:145], v[252:255], v[174:177], v[142:145]
	v_mfma_f32_16x16x32_bf16 v[158:161], v[252:255], v[190:193], v[158:161]
	s_nop 7
	s_nop 1
	s_cmp_le_i32 s60, s4
	s_cbranch_scc1 .Ld16c_nmb1
	v_subrev_u32_e32 v246, 64, v233
	v_cmp_gt_i32_e64 s[74:75], 0, v246
	v_cmp_gt_i32_e64 s[76:77], 1, v246
	v_cmp_gt_i32_e64 s[78:79], 2, v246
	v_cmp_gt_i32_e64 s[80:81], 3, v246
	v_cndmask_b32_e64 v130, v130, v230, s[74:75]
	v_cndmask_b32_e64 v131, v131, v230, s[76:77]
	v_cndmask_b32_e64 v132, v132, v230, s[78:79]
	v_cndmask_b32_e64 v133, v133, v230, s[80:81]
	v_cmp_gt_i32_e64 s[74:75], 16, v246
	v_cmp_gt_i32_e64 s[76:77], 17, v246
	v_cmp_gt_i32_e64 s[78:79], 18, v246
	v_cmp_gt_i32_e64 s[80:81], 19, v246
	v_cndmask_b32_e64 v134, v134, v230, s[74:75]
	v_cndmask_b32_e64 v135, v135, v230, s[76:77]
	v_cndmask_b32_e64 v136, v136, v230, s[78:79]
	v_cndmask_b32_e64 v137, v137, v230, s[80:81]
	v_cmp_gt_i32_e64 s[74:75], 32, v246
	v_cmp_gt_i32_e64 s[76:77], 33, v246
	v_cmp_gt_i32_e64 s[78:79], 34, v246
	v_cmp_gt_i32_e64 s[80:81], 35, v246
	v_cndmask_b32_e64 v138, v138, v230, s[74:75]
	v_cndmask_b32_e64 v139, v139, v230, s[76:77]
	v_cndmask_b32_e64 v140, v140, v230, s[78:79]
	v_cndmask_b32_e64 v141, v141, v230, s[80:81]
	v_cmp_gt_i32_e64 s[74:75], 48, v246
	v_cmp_gt_i32_e64 s[76:77], 49, v246
	v_cmp_gt_i32_e64 s[78:79], 50, v246
	v_cmp_gt_i32_e64 s[80:81], 51, v246
	v_cndmask_b32_e64 v142, v142, v230, s[74:75]
	v_cndmask_b32_e64 v143, v143, v230, s[76:77]
	v_cndmask_b32_e64 v144, v144, v230, s[78:79]
	v_cndmask_b32_e64 v145, v145, v230, s[80:81]
	v_cmp_gt_i32_e64 s[74:75], -16, v246
	v_cmp_gt_i32_e64 s[76:77], -15, v246
	v_cmp_gt_i32_e64 s[78:79], -14, v246
	v_cmp_gt_i32_e64 s[80:81], -13, v246
	v_cndmask_b32_e64 v146, v146, v230, s[74:75]
	v_cndmask_b32_e64 v147, v147, v230, s[76:77]
	v_cndmask_b32_e64 v148, v148, v230, s[78:79]
	v_cndmask_b32_e64 v149, v149, v230, s[80:81]
	v_cmp_gt_i32_e64 s[74:75], 0, v246
	v_cmp_gt_i32_e64 s[76:77], 1, v246
	v_cmp_gt_i32_e64 s[78:79], 2, v246
	v_cmp_gt_i32_e64 s[80:81], 3, v246
	v_cndmask_b32_e64 v150, v150, v230, s[74:75]
	v_cndmask_b32_e64 v151, v151, v230, s[76:77]
	v_cndmask_b32_e64 v152, v152, v230, s[78:79]
	v_cndmask_b32_e64 v153, v153, v230, s[80:81]
	v_cmp_gt_i32_e64 s[74:75], 16, v246
	v_cmp_gt_i32_e64 s[76:77], 17, v246
	v_cmp_gt_i32_e64 s[78:79], 18, v246
	v_cmp_gt_i32_e64 s[80:81], 19, v246
	v_cndmask_b32_e64 v154, v154, v230, s[74:75]
	v_cndmask_b32_e64 v155, v155, v230, s[76:77]
	v_cndmask_b32_e64 v156, v156, v230, s[78:79]
	v_cndmask_b32_e64 v157, v157, v230, s[80:81]
	v_cmp_gt_i32_e64 s[74:75], 32, v246
	v_cmp_gt_i32_e64 s[76:77], 33, v246
	v_cmp_gt_i32_e64 s[78:79], 34, v246
	v_cmp_gt_i32_e64 s[80:81], 35, v246
	v_cndmask_b32_e64 v158, v158, v230, s[74:75]
	v_cndmask_b32_e64 v159, v159, v230, s[76:77]
	v_cndmask_b32_e64 v160, v160, v230, s[78:79]
	v_cndmask_b32_e64 v161, v161, v230, s[80:81]
